# sc1 also on the prologue, modreduce and fft8 stores
# speedup vs baseline: 1.0020x; 1.0020x over previous
; #define LAS __attribute__((address_space(3)))
; __device__ __forceinline__ float silu_f(float v) { return v * __builtin_amdgcn_rcpf(1.0f + __expf(-v)); }
; #define LDS_WAIT() asm volatile("s_waitcnt lgkmcnt(0)" ::: "memory")
;     __device__ __forceinline__ const char* b(const pg8::Unit& u) const { return (const char*)ws + boff + (size_t)u.pn * 256 * K_ * 2 + (u.kq < 0 ? 0 : u.kq * (K_ / 4) * 2); }
;     __device__ __forceinline__ const char* b(const pg8::Unit& u) const { return (const char*)ws + boff + (size_t)u.pn * 256 * D * 2; }
;     __device__ __forceinline__ const char* b(const pg8::Unit& u) const { return (const char*)ws + boff + (size_t)u.pn * 256 * D * 2; }
;     __device__ __forceinline__ const char* b(const pg8::Unit& u) const { return (const char*)ws + WS_A + ((size_t)u.pn * 256 * D + (size_t)(u.pm >> 1) * 256) * 2; }
; __device__ __forceinline__ void p0_prologue(Frame& F) {
;     ...
;         for (int it = gw; it < NIT; it += NGW) {
;             const int ks = it % NKS, cg = (it / NKS) % NCG, L = it / (NKS * NCG), k0 = ks * 256;
;             for (int e = lane; e < 9 * 256; e += 64) { const int k = e & 255, b = e >> 8; const float v = (b < 8) ? c[b * D + k0 + k] : cc[k0 + k]; scr[k * 12 + b] = silu_f(v); }
;             LDS_WAIT(); asm volatile("" ::: "memory");
;             f32x4 acc[9];
; #pragma unroll
;             for (int b = 0; b < 9; ++b) acc[b] = (f32x4){0.f, 0.f, 0.f, 0.f};
;             const float* wp = wm + ((size_t)L * D + k0) * MODW + cg * 256 + lane * 4;
; #pragma unroll 8
;             for (int k = 0; k < 256; ++k) {
;                 const f32x4 wv = __builtin_nontemporal_load((const f32x4*)(wp + (size_t)k * MODW));
;                 const f32x4 s0 = *(const LAS f32x4*)(scr + k * 12), s1 = *(const LAS f32x4*)(scr + k * 12 + 4); const float s2 = scr[k * 12 + 8];
;                 acc[0] += wv * s0[0]; acc[1] += wv * s0[1]; acc[2] += wv * s0[2]; acc[3] += wv * s0[3];
;                 acc[4] += wv * s1[0]; acc[5] += wv * s1[1]; acc[6] += wv * s1[2]; acc[7] += wv * s1[3]; acc[8] += wv * s2;
;             }
.LBB0_23:
	v_lshl_add_u64 v[42:43], v[40:41], 0, s[26:27]
	v_add_co_u32_e32 v116, vcc, s30, v42
	global_load_dwordx4 v[48:51], v[42:43], off nt
	s_nop 0
	v_addc_co_u32_e32 v117, vcc, 0, v43, vcc
	v_add_co_u32_e32 v120, vcc, s31, v42
	v_mov_b32_e32 v47, s5
	s_nop 0
	v_addc_co_u32_e32 v121, vcc, 0, v43, vcc
	v_add_co_u32_e32 v124, vcc, s33, v42
	ds_read_b128 v[52:55], v47
	ds_read_b128 v[56:59], v47 offset:16
	ds_read2_b32 v[144:145], v47 offset0:8 offset1:20
	v_addc_co_u32_e32 v125, vcc, 0, v43, vcc
	v_add_co_u32_e32 v128, vcc, s34, v42
	ds_read_b128 v[60:63], v47 offset:48
	ds_read_b128 v[64:67], v47 offset:64
	v_addc_co_u32_e32 v129, vcc, 0, v43, vcc
	v_add_co_u32_e32 v132, vcc, s35, v42
	ds_read_b128 v[68:71], v47 offset:96
	ds_read_b128 v[72:75], v47 offset:112
	ds_read2_b32 v[146:147], v47 offset0:32 offset1:44
	v_addc_co_u32_e32 v133, vcc, 0, v43, vcc
	v_add_co_u32_e32 v136, vcc, s36, v42
	ds_read_b128 v[76:79], v47 offset:144
	ds_read_b128 v[80:83], v47 offset:160
	v_addc_co_u32_e32 v137, vcc, 0, v43, vcc
	v_add_co_u32_e32 v42, vcc, s37, v42
	ds_read_b128 v[84:87], v47 offset:192
	ds_read_b128 v[88:91], v47 offset:208
	v_addc_co_u32_e32 v43, vcc, 0, v43, vcc
	ds_read2_b32 v[148:149], v47 offset0:56 offset1:68
	ds_read_b128 v[92:95], v47 offset:240
	ds_read_b128 v[96:99], v47 offset:256
	ds_read_b128 v[100:103], v47 offset:288
	ds_read_b128 v[104:107], v47 offset:304
	ds_read2_b32 v[150:151], v47 offset0:80 offset1:92
	ds_read_b128 v[108:111], v47 offset:336
	ds_read_b128 v[112:115], v47 offset:352
	global_load_dwordx4 v[116:119], v[116:117], off nt
	s_nop 0
	global_load_dwordx4 v[120:123], v[120:121], off nt
	s_nop 0
	global_load_dwordx4 v[124:127], v[124:125], off nt
	s_nop 0
	global_load_dwordx4 v[128:131], v[128:129], off nt
	s_nop 0
	global_load_dwordx4 v[132:135], v[132:133], off nt
	s_nop 0
	global_load_dwordx4 v[136:139], v[136:137], off nt
	s_nop 0
	global_load_dwordx4 v[140:143], v[42:43], off nt
	s_waitcnt lgkmcnt(14)
	v_mov_b32_e32 v42, v55
	v_mov_b32_e32 v152, v59
	v_mov_b32_e32 v154, v63
	v_mov_b32_e32 v156, v67
	v_mov_b32_e32 v158, v145
	v_mov_b32_e32 v160, v71
	s_waitcnt lgkmcnt(13)
	v_mov_b32_e32 v162, v75
	s_waitcnt lgkmcnt(11)
	v_mov_b32_e32 v164, v79
	s_waitcnt lgkmcnt(10)
	v_mov_b32_e32 v166, v83
	v_mov_b32_e32 v168, v147
	s_waitcnt lgkmcnt(9)
	v_mov_b32_e32 v170, v87
	s_waitcnt lgkmcnt(8)
	v_mov_b32_e32 v172, v91
	s_waitcnt lgkmcnt(6)
	v_mov_b32_e32 v174, v95
	s_waitcnt lgkmcnt(5)
	v_mov_b32_e32 v176, v99
	v_mov_b32_e32 v178, v149
	s_add_u32 s26, s26, 0x60000
	s_waitcnt lgkmcnt(4)
	v_mov_b32_e32 v180, v103
	s_waitcnt lgkmcnt(3)
	v_mov_b32_e32 v182, v107
	s_addc_u32 s27, s27, 0
	s_addk_i32 s5, 0x180
	s_waitcnt lgkmcnt(1)
	v_mov_b32_e32 v184, v111
	s_waitcnt lgkmcnt(0)
	v_mov_b32_e32 v186, v115
	v_mov_b32_e32 v188, v151
	s_cmp_eq_u32 s26, 0xc00000
	s_waitcnt vmcnt(7)
	v_pk_fma_f32 v[22:23], v[50:51], v[52:53], v[22:23] op_sel_hi:[1,0,1]
	v_pk_fma_f32 v[20:21], v[48:49], v[52:53], v[20:21] op_sel_hi:[1,0,1]
	v_pk_fma_f32 v[34:35], v[50:51], v[52:53], v[34:35] op_sel:[0,1,0]
	v_pk_fma_f32 v[32:33], v[48:49], v[52:53], v[32:33] op_sel:[0,1,0]
	v_pk_fma_f32 v[28:29], v[48:49], v[54:55], v[28:29] op_sel_hi:[1,0,1]
	v_pk_fma_f32 v[30:31], v[50:51], v[54:55], v[30:31] op_sel_hi:[1,0,1]
	v_pk_fma_f32 v[26:27], v[50:51], v[56:57], v[26:27] op_sel_hi:[1,0,1]
	v_pk_fma_f32 v[24:25], v[48:49], v[56:57], v[24:25] op_sel_hi:[1,0,1]
	v_pk_fma_f32 v[18:19], v[50:51], v[56:57], v[18:19] op_sel:[0,1,0]
	v_pk_fma_f32 v[16:17], v[48:49], v[56:57], v[16:17] op_sel:[0,1,0]
	v_pk_fma_f32 v[12:13], v[48:49], v[58:59], v[12:13] op_sel_hi:[1,0,1]
	v_pk_fma_f32 v[14:15], v[50:51], v[58:59], v[14:15] op_sel_hi:[1,0,1]
	v_pk_fma_f32 v[8:9], v[48:49], v[42:43], v[8:9] op_sel_hi:[1,0,1]
	v_pk_fma_f32 v[10:11], v[50:51], v[42:43], v[10:11] op_sel_hi:[1,0,1]
	v_pk_fma_f32 v[4:5], v[48:49], v[152:153], v[4:5] op_sel_hi:[1,0,1]
	v_pk_fma_f32 v[6:7], v[50:51], v[152:153], v[6:7] op_sel_hi:[1,0,1]
	v_pk_fma_f32 v[0:1], v[48:49], v[144:145], v[0:1] op_sel_hi:[1,0,1]
	v_pk_fma_f32 v[2:3], v[50:51], v[144:145], v[2:3] op_sel_hi:[1,0,1]
	s_waitcnt vmcnt(6)
	v_pk_fma_f32 v[20:21], v[116:117], v[60:61], v[20:21] op_sel_hi:[1,0,1]
	v_pk_fma_f32 v[22:23], v[118:119], v[60:61], v[22:23] op_sel_hi:[1,0,1]
	v_pk_fma_f32 v[32:33], v[116:117], v[60:61], v[32:33] op_sel:[0,1,0]
	v_pk_fma_f32 v[34:35], v[118:119], v[60:61], v[34:35] op_sel:[0,1,0]
	v_pk_fma_f32 v[28:29], v[116:117], v[62:63], v[28:29] op_sel_hi:[1,0,1]
	v_pk_fma_f32 v[30:31], v[118:119], v[62:63], v[30:31] op_sel_hi:[1,0,1]
	v_pk_fma_f32 v[24:25], v[116:117], v[64:65], v[24:25] op_sel_hi:[1,0,1]
	v_pk_fma_f32 v[26:27], v[118:119], v[64:65], v[26:27] op_sel_hi:[1,0,1]
	v_pk_fma_f32 v[16:17], v[116:117], v[64:65], v[16:17] op_sel:[0,1,0]
	v_pk_fma_f32 v[18:19], v[118:119], v[64:65], v[18:19] op_sel:[0,1,0]
	v_pk_fma_f32 v[12:13], v[116:117], v[66:67], v[12:13] op_sel_hi:[1,0,1]
	v_pk_fma_f32 v[14:15], v[118:119], v[66:67], v[14:15] op_sel_hi:[1,0,1]
	v_pk_fma_f32 v[8:9], v[116:117], v[154:155], v[8:9] op_sel_hi:[1,0,1]
	v_pk_fma_f32 v[10:11], v[118:119], v[154:155], v[10:11] op_sel_hi:[1,0,1]
	v_pk_fma_f32 v[4:5], v[116:117], v[156:157], v[4:5] op_sel_hi:[1,0,1]
	v_pk_fma_f32 v[6:7], v[118:119], v[156:157], v[6:7] op_sel_hi:[1,0,1]
	v_pk_fma_f32 v[0:1], v[116:117], v[158:159], v[0:1] op_sel_hi:[1,0,1]
	v_pk_fma_f32 v[2:3], v[118:119], v[158:159], v[2:3] op_sel_hi:[1,0,1]
	s_waitcnt vmcnt(5)
; #define LAS __attribute__((address_space(3)))
; __device__ __forceinline__ void p0_prologue(Frame& F) {
;     ...
;             for (int k = 0; k < 256; ++k) {
;                 const f32x4 wv = __builtin_nontemporal_load((const f32x4*)(wp + (size_t)k * MODW));
;                 const f32x4 s0 = *(const LAS f32x4*)(scr + k * 12), s1 = *(const LAS f32x4*)(scr + k * 12 + 4); const float s2 = scr[k * 12 + 8];
;                 acc[0] += wv * s0[0]; acc[1] += wv * s0[1]; acc[2] += wv * s0[2]; acc[3] += wv * s0[3];
;                 acc[4] += wv * s1[0]; acc[5] += wv * s1[1]; acc[6] += wv * s1[2]; acc[7] += wv * s1[3]; acc[8] += wv * s2;
;             }
	v_pk_fma_f32 v[22:23], v[122:123], v[68:69], v[22:23] op_sel_hi:[1,0,1]
	v_pk_fma_f32 v[20:21], v[120:121], v[68:69], v[20:21] op_sel_hi:[1,0,1]
	v_pk_fma_f32 v[34:35], v[122:123], v[68:69], v[34:35] op_sel:[0,1,0]
	v_pk_fma_f32 v[32:33], v[120:121], v[68:69], v[32:33] op_sel:[0,1,0]
	v_pk_fma_f32 v[30:31], v[122:123], v[70:71], v[30:31] op_sel_hi:[1,0,1]
	v_pk_fma_f32 v[28:29], v[120:121], v[70:71], v[28:29] op_sel_hi:[1,0,1]
	v_pk_fma_f32 v[10:11], v[122:123], v[160:161], v[10:11] op_sel_hi:[1,0,1]
	v_pk_fma_f32 v[8:9], v[120:121], v[160:161], v[8:9] op_sel_hi:[1,0,1]
	v_pk_fma_f32 v[26:27], v[122:123], v[72:73], v[26:27] op_sel_hi:[1,0,1]
	v_pk_fma_f32 v[24:25], v[120:121], v[72:73], v[24:25] op_sel_hi:[1,0,1]
	v_pk_fma_f32 v[18:19], v[122:123], v[72:73], v[18:19] op_sel:[0,1,0]
	v_pk_fma_f32 v[16:17], v[120:121], v[72:73], v[16:17] op_sel:[0,1,0]
	v_pk_fma_f32 v[14:15], v[122:123], v[74:75], v[14:15] op_sel_hi:[1,0,1]
	v_pk_fma_f32 v[12:13], v[120:121], v[74:75], v[12:13] op_sel_hi:[1,0,1]
	v_pk_fma_f32 v[6:7], v[122:123], v[162:163], v[6:7] op_sel_hi:[1,0,1]
	v_pk_fma_f32 v[4:5], v[120:121], v[162:163], v[4:5] op_sel_hi:[1,0,1]
	v_pk_fma_f32 v[2:3], v[122:123], v[146:147], v[2:3] op_sel_hi:[1,0,1]
	v_pk_fma_f32 v[0:1], v[120:121], v[146:147], v[0:1] op_sel_hi:[1,0,1]
	s_waitcnt vmcnt(4)
	v_pk_fma_f32 v[22:23], v[126:127], v[76:77], v[22:23] op_sel_hi:[1,0,1]
	v_pk_fma_f32 v[20:21], v[124:125], v[76:77], v[20:21] op_sel_hi:[1,0,1]
	v_pk_fma_f32 v[34:35], v[126:127], v[76:77], v[34:35] op_sel:[0,1,0]
	v_pk_fma_f32 v[32:33], v[124:125], v[76:77], v[32:33] op_sel:[0,1,0]
	v_pk_fma_f32 v[30:31], v[126:127], v[78:79], v[30:31] op_sel_hi:[1,0,1]
	v_pk_fma_f32 v[28:29], v[124:125], v[78:79], v[28:29] op_sel_hi:[1,0,1]
	v_pk_fma_f32 v[26:27], v[126:127], v[80:81], v[26:27] op_sel_hi:[1,0,1]
	v_pk_fma_f32 v[24:25], v[124:125], v[80:81], v[24:25] op_sel_hi:[1,0,1]
	v_pk_fma_f32 v[18:19], v[126:127], v[80:81], v[18:19] op_sel:[0,1,0]
	v_pk_fma_f32 v[16:17], v[124:125], v[80:81], v[16:17] op_sel:[0,1,0]
	v_pk_fma_f32 v[14:15], v[126:127], v[82:83], v[14:15] op_sel_hi:[1,0,1]
	v_pk_fma_f32 v[12:13], v[124:125], v[82:83], v[12:13] op_sel_hi:[1,0,1]
	v_pk_fma_f32 v[10:11], v[126:127], v[164:165], v[10:11] op_sel_hi:[1,0,1]
	v_pk_fma_f32 v[8:9], v[124:125], v[164:165], v[8:9] op_sel_hi:[1,0,1]
	v_pk_fma_f32 v[6:7], v[126:127], v[166:167], v[6:7] op_sel_hi:[1,0,1]
	v_pk_fma_f32 v[4:5], v[124:125], v[166:167], v[4:5] op_sel_hi:[1,0,1]
	v_pk_fma_f32 v[2:3], v[126:127], v[168:169], v[2:3] op_sel_hi:[1,0,1]
	v_pk_fma_f32 v[0:1], v[124:125], v[168:169], v[0:1] op_sel_hi:[1,0,1]
	s_waitcnt vmcnt(3)
	v_pk_fma_f32 v[22:23], v[130:131], v[84:85], v[22:23] op_sel_hi:[1,0,1]
	v_pk_fma_f32 v[20:21], v[128:129], v[84:85], v[20:21] op_sel_hi:[1,0,1]
	v_pk_fma_f32 v[34:35], v[130:131], v[84:85], v[34:35] op_sel:[0,1,0]
	v_pk_fma_f32 v[32:33], v[128:129], v[84:85], v[32:33] op_sel:[0,1,0]
	v_pk_fma_f32 v[30:31], v[130:131], v[86:87], v[30:31] op_sel_hi:[1,0,1]
	v_pk_fma_f32 v[28:29], v[128:129], v[86:87], v[28:29] op_sel_hi:[1,0,1]
	v_pk_fma_f32 v[26:27], v[130:131], v[88:89], v[26:27] op_sel_hi:[1,0,1]
	v_pk_fma_f32 v[24:25], v[128:129], v[88:89], v[24:25] op_sel_hi:[1,0,1]
	v_pk_fma_f32 v[18:19], v[130:131], v[88:89], v[18:19] op_sel:[0,1,0]
	v_pk_fma_f32 v[16:17], v[128:129], v[88:89], v[16:17] op_sel:[0,1,0]
	v_pk_fma_f32 v[14:15], v[130:131], v[90:91], v[14:15] op_sel_hi:[1,0,1]
	v_pk_fma_f32 v[12:13], v[128:129], v[90:91], v[12:13] op_sel_hi:[1,0,1]
	v_pk_fma_f32 v[10:11], v[130:131], v[170:171], v[10:11] op_sel_hi:[1,0,1]
	v_pk_fma_f32 v[8:9], v[128:129], v[170:171], v[8:9] op_sel_hi:[1,0,1]
	v_pk_fma_f32 v[6:7], v[130:131], v[172:173], v[6:7] op_sel_hi:[1,0,1]
	v_pk_fma_f32 v[4:5], v[128:129], v[172:173], v[4:5] op_sel_hi:[1,0,1]
	v_pk_fma_f32 v[2:3], v[130:131], v[148:149], v[2:3] op_sel_hi:[1,0,1]
	v_pk_fma_f32 v[0:1], v[128:129], v[148:149], v[0:1] op_sel_hi:[1,0,1]
	s_waitcnt vmcnt(2)
	v_pk_fma_f32 v[22:23], v[134:135], v[92:93], v[22:23] op_sel_hi:[1,0,1]
	v_pk_fma_f32 v[20:21], v[132:133], v[92:93], v[20:21] op_sel_hi:[1,0,1]
	v_pk_fma_f32 v[34:35], v[134:135], v[92:93], v[34:35] op_sel:[0,1,0]
	v_pk_fma_f32 v[32:33], v[132:133], v[92:93], v[32:33] op_sel:[0,1,0]
	v_pk_fma_f32 v[30:31], v[134:135], v[94:95], v[30:31] op_sel_hi:[1,0,1]
	v_pk_fma_f32 v[28:29], v[132:133], v[94:95], v[28:29] op_sel_hi:[1,0,1]
	v_pk_fma_f32 v[10:11], v[134:135], v[174:175], v[10:11] op_sel_hi:[1,0,1]
	v_pk_fma_f32 v[8:9], v[132:133], v[174:175], v[8:9] op_sel_hi:[1,0,1]
	v_pk_fma_f32 v[26:27], v[134:135], v[96:97], v[26:27] op_sel_hi:[1,0,1]
	v_pk_fma_f32 v[24:25], v[132:133], v[96:97], v[24:25] op_sel_hi:[1,0,1]
	v_pk_fma_f32 v[18:19], v[134:135], v[96:97], v[18:19] op_sel:[0,1,0]
	v_pk_fma_f32 v[16:17], v[132:133], v[96:97], v[16:17] op_sel:[0,1,0]
	v_pk_fma_f32 v[14:15], v[134:135], v[98:99], v[14:15] op_sel_hi:[1,0,1]
	v_pk_fma_f32 v[12:13], v[132:133], v[98:99], v[12:13] op_sel_hi:[1,0,1]
	v_pk_fma_f32 v[6:7], v[134:135], v[176:177], v[6:7] op_sel_hi:[1,0,1]
	v_pk_fma_f32 v[4:5], v[132:133], v[176:177], v[4:5] op_sel_hi:[1,0,1]
	v_pk_fma_f32 v[2:3], v[134:135], v[178:179], v[2:3] op_sel_hi:[1,0,1]
	v_pk_fma_f32 v[0:1], v[132:133], v[178:179], v[0:1] op_sel_hi:[1,0,1]
	s_waitcnt vmcnt(1)
; #define LAS __attribute__((address_space(3)))
; #define LDS_WAIT() asm volatile("s_waitcnt lgkmcnt(0)" ::: "memory")
;     __device__ __forceinline__ const char* b(const pg8::Unit& u) const { return (const char*)ws + boff + (size_t)u.pn * 256 * K_ * 2 + (u.kq < 0 ? 0 : u.kq * (K_ / 4) * 2); }
;     __device__ __forceinline__ const char* b(const pg8::Unit& u) const { return (const char*)ws + boff + (size_t)u.pn * 256 * D * 2; }
;     __device__ __forceinline__ const char* b(const pg8::Unit& u) const { return (const char*)ws + boff + (size_t)u.pn * 256 * D * 2; }
;     __device__ __forceinline__ const char* b(const pg8::Unit& u) const { return (const char*)ws + WS_A + ((size_t)u.pn * 256 * D + (size_t)(u.pm >> 1) * 256) * 2; }
; __device__ __forceinline__ void p0_prologue(Frame& F) {
;     ...
;             for (int k = 0; k < 256; ++k) {
;                 const f32x4 wv = __builtin_nontemporal_load((const f32x4*)(wp + (size_t)k * MODW));
;                 const f32x4 s0 = *(const LAS f32x4*)(scr + k * 12), s1 = *(const LAS f32x4*)(scr + k * 12 + 4); const float s2 = scr[k * 12 + 8];
;                 acc[0] += wv * s0[0]; acc[1] += wv * s0[1]; acc[2] += wv * s0[2]; acc[3] += wv * s0[3];
;                 acc[4] += wv * s1[0]; acc[5] += wv * s1[1]; acc[6] += wv * s1[2]; acc[7] += wv * s1[3]; acc[8] += wv * s2;
;             }
; #pragma unroll
;             for (int b = 0; b < 9; ++b) *(f32x4*)(modp + (((size_t)ks * DEPTH + L) * 9 + b) * MODW + cg * 256 + lane * 4) = acc[b];
;             LDS_WAIT(); asm volatile("" ::: "memory");
;         }
	v_pk_fma_f32 v[22:23], v[138:139], v[100:101], v[22:23] op_sel_hi:[1,0,1]
	v_pk_fma_f32 v[20:21], v[136:137], v[100:101], v[20:21] op_sel_hi:[1,0,1]
	v_pk_fma_f32 v[34:35], v[138:139], v[100:101], v[34:35] op_sel:[0,1,0]
	v_pk_fma_f32 v[32:33], v[136:137], v[100:101], v[32:33] op_sel:[0,1,0]
	v_pk_fma_f32 v[30:31], v[138:139], v[102:103], v[30:31] op_sel_hi:[1,0,1]
	v_pk_fma_f32 v[28:29], v[136:137], v[102:103], v[28:29] op_sel_hi:[1,0,1]
	v_pk_fma_f32 v[26:27], v[138:139], v[104:105], v[26:27] op_sel_hi:[1,0,1]
	v_pk_fma_f32 v[24:25], v[136:137], v[104:105], v[24:25] op_sel_hi:[1,0,1]
	v_pk_fma_f32 v[18:19], v[138:139], v[104:105], v[18:19] op_sel:[0,1,0]
	v_pk_fma_f32 v[16:17], v[136:137], v[104:105], v[16:17] op_sel:[0,1,0]
	v_pk_fma_f32 v[14:15], v[138:139], v[106:107], v[14:15] op_sel_hi:[1,0,1]
	v_pk_fma_f32 v[12:13], v[136:137], v[106:107], v[12:13] op_sel_hi:[1,0,1]
	v_pk_fma_f32 v[10:11], v[138:139], v[180:181], v[10:11] op_sel_hi:[1,0,1]
	v_pk_fma_f32 v[8:9], v[136:137], v[180:181], v[8:9] op_sel_hi:[1,0,1]
	v_pk_fma_f32 v[6:7], v[138:139], v[182:183], v[6:7] op_sel_hi:[1,0,1]
	v_pk_fma_f32 v[4:5], v[136:137], v[182:183], v[4:5] op_sel_hi:[1,0,1]
	v_pk_fma_f32 v[2:3], v[138:139], v[150:151], v[2:3] op_sel_hi:[1,0,1]
	v_pk_fma_f32 v[0:1], v[136:137], v[150:151], v[0:1] op_sel_hi:[1,0,1]
	s_waitcnt vmcnt(0)
	v_pk_fma_f32 v[22:23], v[142:143], v[108:109], v[22:23] op_sel_hi:[1,0,1]
	v_pk_fma_f32 v[20:21], v[140:141], v[108:109], v[20:21] op_sel_hi:[1,0,1]
	v_pk_fma_f32 v[34:35], v[142:143], v[108:109], v[34:35] op_sel:[0,1,0]
	v_pk_fma_f32 v[32:33], v[140:141], v[108:109], v[32:33] op_sel:[0,1,0]
	v_pk_fma_f32 v[30:31], v[142:143], v[110:111], v[30:31] op_sel_hi:[1,0,1]
	v_pk_fma_f32 v[28:29], v[140:141], v[110:111], v[28:29] op_sel_hi:[1,0,1]
	v_pk_fma_f32 v[10:11], v[142:143], v[184:185], v[10:11] op_sel_hi:[1,0,1]
	v_pk_fma_f32 v[8:9], v[140:141], v[184:185], v[8:9] op_sel_hi:[1,0,1]
	v_pk_fma_f32 v[26:27], v[142:143], v[112:113], v[26:27] op_sel_hi:[1,0,1]
	v_pk_fma_f32 v[24:25], v[140:141], v[112:113], v[24:25] op_sel_hi:[1,0,1]
	v_pk_fma_f32 v[18:19], v[142:143], v[112:113], v[18:19] op_sel:[0,1,0]
	v_pk_fma_f32 v[16:17], v[140:141], v[112:113], v[16:17] op_sel:[0,1,0]
	v_pk_fma_f32 v[14:15], v[142:143], v[114:115], v[14:15] op_sel_hi:[1,0,1]
	v_pk_fma_f32 v[12:13], v[140:141], v[114:115], v[12:13] op_sel_hi:[1,0,1]
	v_pk_fma_f32 v[6:7], v[142:143], v[186:187], v[6:7] op_sel_hi:[1,0,1]
	v_pk_fma_f32 v[4:5], v[140:141], v[186:187], v[4:5] op_sel_hi:[1,0,1]
	v_pk_fma_f32 v[2:3], v[142:143], v[188:189], v[2:3] op_sel_hi:[1,0,1]
	v_pk_fma_f32 v[0:1], v[140:141], v[188:189], v[0:1] op_sel_hi:[1,0,1]
	s_cbranch_scc0 .LBB0_23
	s_ashr_i32 s5, s4, 31
	s_lshl_b64 s[4:5], s[4:5], 2
	s_add_u32 s4, s4, s39
	s_addc_u32 s26, s5, s40
	v_lshl_add_u64 v[40:41], s[16:17], 2, v[36:37]
	v_mad_u64_u32 v[40:41], s[4:5], s4, v46, v[40:41]
	s_mul_i32 s26, s26, 0x6c000
	v_add_u32_e32 v41, s26, v41
	global_store_dwordx4 v[40:41], v[20:23], off sc1
	s_add_i32 s38, s38, s7
	s_cmpk_gt_i32 s38, 0x5ff
	v_add_co_u32_e32 v20, vcc, s30, v40
	s_nop 1
	v_addc_co_u32_e32 v21, vcc, 0, v41, vcc
	global_store_dwordx4 v[20:21], v[32:35], off sc1
	v_add_co_u32_e32 v20, vcc, s31, v40
	s_nop 1
	v_addc_co_u32_e32 v21, vcc, 0, v41, vcc
	global_store_dwordx4 v[20:21], v[28:31], off sc1
	v_add_co_u32_e32 v20, vcc, s33, v40
	s_nop 1
	v_addc_co_u32_e32 v21, vcc, 0, v41, vcc
	global_store_dwordx4 v[20:21], v[8:11], off sc1
	s_nop 1
	v_add_co_u32_e32 v8, vcc, s34, v40
	s_nop 1
	v_addc_co_u32_e32 v9, vcc, 0, v41, vcc
	global_store_dwordx4 v[8:9], v[24:27], off sc1
	v_add_co_u32_e32 v8, vcc, s35, v40
	s_nop 1
	v_addc_co_u32_e32 v9, vcc, 0, v41, vcc
	global_store_dwordx4 v[8:9], v[16:19], off sc1
	v_add_co_u32_e32 v8, vcc, s36, v40
	s_nop 1
	v_addc_co_u32_e32 v9, vcc, 0, v41, vcc
	global_store_dwordx4 v[8:9], v[12:15], off sc1
	v_add_co_u32_e32 v8, vcc, 0x54000, v40
	s_nop 1
	v_addc_co_u32_e32 v9, vcc, 0, v41, vcc
	global_store_dwordx4 v[8:9], v[4:7], off sc1
	s_nop 1
	v_add_co_u32_e32 v4, vcc, 0x60000, v40
	s_nop 1
	v_addc_co_u32_e32 v5, vcc, 0, v41, vcc
	global_store_dwordx4 v[4:5], v[0:3], off sc1
	s_waitcnt lgkmcnt(0)
	s_cbranch_scc0 .LBB0_19

; #define LAS __attribute__((address_space(3)))
; __device__ __forceinline__ unsigned cvt_pk_bf16(float lo, float hi) { const f32x2 v = {lo, hi}; return __builtin_bit_cast(unsigned, __builtin_convertvector(v, bf16x2_t)); }
; #define LDS_WAIT() asm volatile("s_waitcnt lgkmcnt(0)" ::: "memory")
; __device__ __forceinline__ void p0_transpose_item(const float* W, int K, int N, bf16_t* WT, int k0, int n0, int drow0, LAS float* scr, int lane) {
;     const int kk = lane >> 3, nq = (lane & 7) * 4;
;     f32x4 v[8];
; #pragma unroll
;     for (int i = 0; i < 8; ++i) v[i] = __builtin_nontemporal_load((const f32x4*)(W + (size_t)(k0 + 8 * i + kk) * N + n0 + nq));
; #pragma unroll
;     for (int i = 0; i < 8; ++i) { LAS float* d = scr + (8 * i + kk) * 33 + nq; d[0] = v[i].x; d[1] = v[i].y; d[2] = v[i].z; d[3] = v[i].w; }
;     LDS_WAIT(); asm volatile("" ::: "memory");
;     const int c = lane & 7;
; #pragma unroll
;     for (int j = 0; j < 4; ++j) { const int n = (lane >> 3) + 8 * j; const LAS float* s = scr + (8 * c) * 33 + n;
;         u32x4 o; o.x = cvt_pk_bf16(s[0 * 33], s[1 * 33]); o.y = cvt_pk_bf16(s[2 * 33], s[3 * 33]); o.z = cvt_pk_bf16(s[4 * 33], s[5 * 33]); o.w = cvt_pk_bf16(s[6 * 33], s[7 * 33]);
;         *(u32x4*)(WT + (size_t)(drow0 + n) * K + k0 + 8 * c) = o; }
;     LDS_WAIT(); asm volatile("" ::: "memory");
; }
; __device__ __forceinline__ void p0_prologue(Frame& F) {
;     ...
;             { const int jj = r / I_D; r -= jj * I_D; const int j = 2 * jj; const int nblk = D / 32, kb = r / nblk, nb = r % nblk;
;                 p0_transpose_item(F.in[I_WDN] + (size_t)j * DFF * D, DFF, D, (bf16_t*)(ws + WS_WDN) + (size_t)j * D * DFF, 64 * kb, 32 * nb, 32 * nb, scr, lane); }
.LBB0_30:
	s_cmpk_gt_u32 s3, 0x5fff
	s_cbranch_scc0 .LBB0_32
	s_add_i32 s0, s3, 0xffffa000
	s_cmpk_gt_u32 s0, 0x15ff
	s_cselect_b32 s0, 0xea00, 0
	s_cselect_b32 s1, 2, 0
	s_add_i32 s0, s0, s3
	s_add_i32 s0, s0, 0xa000
	s_sext_i32_i16 s4, s0
	s_bfe_u32 s4, s4, 0x60019
	s_add_i32 s4, s0, s4
	s_sext_i32_i16 s5, s4
	s_and_b32 s4, s4, 0xffc0
	s_sub_i32 s0, s0, s4
	s_mul_i32 s4, s1, 0x2c00000
	s_add_u32 s38, s60, s4
	s_addc_u32 s39, s61, 0
	s_mul_i32 s1, s1, 0x1600000
	s_sext_i32_i16 s0, s0
	s_add_u32 s40, s10, s1
	s_addc_u32 s41, s11, 0
	s_lshl_b32 s0, s0, 5
	s_ashr_i32 s1, s0, 31
	s_and_b32 s4, s5, 0xffffffc0
	s_lshl_b64 s[36:37], s[0:1], 2
	v_add_u32_e32 v28, s4, v8
	s_add_u32 s36, s38, s36
	s_addc_u32 s37, s39, s37
	v_ashrrev_i32_e32 v29, 31, v28
	v_lshl_add_u64 v[30:31], s[36:37], 0, v[0:1]
	v_lshlrev_b64 v[28:29], 13, v[28:29]
	v_lshl_add_u64 v[58:59], v[30:31], 0, v[28:29]
	v_add_co_u32_e32 v32, vcc, s26, v58
	s_ashr_i32 s5, s4, 31
	s_nop 0
	v_addc_co_u32_e32 v33, vcc, 0, v59, vcc
	v_add_co_u32_e32 v36, vcc, s27, v58
	global_load_dwordx4 v[28:31], v[58:59], off nt
	s_nop 0
	global_load_dwordx4 v[32:35], v[32:33], off nt
	v_addc_co_u32_e32 v37, vcc, 0, v59, vcc
	v_add_co_u32_e32 v40, vcc, s28, v58
	s_lshl_b64 s[4:5], s[4:5], 1
	s_nop 0
	v_addc_co_u32_e32 v41, vcc, 0, v59, vcc
	v_add_co_u32_e32 v46, vcc, s29, v58
	global_load_dwordx4 v[36:39], v[36:37], off nt
	s_nop 0
	global_load_dwordx4 v[40:43], v[40:41], off nt
	v_addc_co_u32_e32 v47, vcc, 0, v59, vcc
	v_add_co_u32_e32 v50, vcc, s30, v58
	s_add_u32 s4, s40, s4
	s_nop 0
	v_addc_co_u32_e32 v51, vcc, 0, v59, vcc
	global_load_dwordx4 v[46:49], v[46:47], off nt
	s_nop 0
	global_load_dwordx4 v[50:53], v[50:51], off nt
	v_add_co_u32_e32 v54, vcc, s31, v58
	v_mov_b32_e32 v7, v1
	s_nop 0
	v_addc_co_u32_e32 v55, vcc, 0, v59, vcc
	global_load_dwordx4 v[54:57], v[54:55], off nt
	v_add_co_u32_e32 v58, vcc, s33, v58
	s_addc_u32 s5, s41, s5
	s_nop 0
	v_addc_co_u32_e32 v59, vcc, 0, v59, vcc
	global_load_dwordx4 v[58:61], v[58:59], off nt
	v_add_u32_e32 v45, s0, v8
	v_lshl_add_u64 v[62:63], s[4:5], 0, v[6:7]
	v_add_u32_e32 v64, s0, v9
	v_add_u32_e32 v7, s0, v10
	s_waitcnt vmcnt(7)
	ds_write2_b32 v13, v28, v29 offset1:1
	ds_write2_b32 v13, v30, v31 offset0:2 offset1:3
	s_waitcnt vmcnt(6)
	ds_write2_b32 v14, v32, v33 offset1:1
	ds_write2_b32 v15, v34, v35 offset1:1
	s_waitcnt vmcnt(5)
	ds_write2_b32 v16, v36, v37 offset1:1
	ds_write2_b32 v17, v38, v39 offset1:1
	s_waitcnt vmcnt(4)
	ds_write2_b32 v18, v40, v41 offset1:1
	ds_write2_b32 v19, v42, v43 offset1:1
	s_waitcnt vmcnt(3)
	ds_write2_b32 v20, v46, v47 offset1:1
	ds_write2_b32 v21, v48, v49 offset1:1
	s_waitcnt vmcnt(2)
	ds_write2_b32 v22, v50, v51 offset1:1
	ds_write2_b32 v23, v52, v53 offset1:1
	s_waitcnt vmcnt(1)
	ds_write2_b32 v24, v54, v55 offset1:1
	ds_write2_b32 v25, v56, v57 offset1:1
	s_waitcnt vmcnt(0)
	ds_write2_b32 v26, v58, v59 offset1:1
	ds_write2_b32 v27, v60, v61 offset1:1
	s_waitcnt lgkmcnt(0)
	ds_read2_b32 v[32:33], v12 offset0:33 offset1:41
	ds_read2_b32 v[34:35], v12 offset1:8
	ds_read2_b32 v[36:37], v12 offset0:66 offset1:74
	ds_read2_b32 v[38:39], v12 offset0:99 offset1:107
	ds_read2_b32 v[40:41], v12 offset0:132 offset1:140
	ds_read2_b32 v[42:43], v12 offset0:165 offset1:173
	ds_read2_b32 v[46:47], v12 offset0:198 offset1:206
	ds_read2_b32 v[48:49], v12 offset0:231 offset1:239
	v_mad_i64_i32 v[50:51], s[4:5], v45, s34, v[62:63]
	s_waitcnt lgkmcnt(6)
	v_cvt_pk_bf16_f32 v28, v34, v32
	s_waitcnt lgkmcnt(4)
	v_cvt_pk_bf16_f32 v29, v36, v38
	s_waitcnt lgkmcnt(2)
	v_cvt_pk_bf16_f32 v30, v40, v42
	s_waitcnt lgkmcnt(0)
	v_cvt_pk_bf16_f32 v31, v46, v48
	global_store_dwordx4 v[50:51], v[28:31], off sc1
	v_cvt_pk_bf16_f32 v32, v35, v33
	v_cvt_pk_bf16_f32 v33, v37, v39
	v_cvt_pk_bf16_f32 v34, v41, v43
	v_cvt_pk_bf16_f32 v35, v47, v49
	ds_read2_b32 v[36:37], v12 offset0:49 offset1:57
	ds_read2_b32 v[38:39], v12 offset0:16 offset1:24
	ds_read2_b32 v[40:41], v12 offset0:82 offset1:90
	ds_read2_b32 v[42:43], v12 offset0:115 offset1:123
	ds_read2_b32 v[46:47], v12 offset0:148 offset1:156
	ds_read2_b32 v[48:49], v12 offset0:181 offset1:189
	ds_read2_b32 v[50:51], v12 offset0:214 offset1:222
	ds_read2_b32 v[52:53], v12 offset0:247 offset1:255
	v_mad_i64_i32 v[28:29], s[4:5], v64, s34, v[62:63]
	global_store_dwordx4 v[28:29], v[32:35], off sc1
	s_waitcnt lgkmcnt(6)
	v_cvt_pk_bf16_f32 v28, v38, v36
	s_waitcnt lgkmcnt(4)
	v_cvt_pk_bf16_f32 v29, v40, v42
	s_waitcnt lgkmcnt(2)
	v_cvt_pk_bf16_f32 v30, v46, v48
	s_waitcnt lgkmcnt(0)
	v_cvt_pk_bf16_f32 v31, v50, v52
	v_mad_i64_i32 v[32:33], s[4:5], v7, s34, v[62:63]
	v_add_u32_e32 v7, s0, v11
	global_store_dwordx4 v[32:33], v[28:31], off sc1
	v_mad_i64_i32 v[32:33], s[0:1], v7, s34, v[62:63]
	s_nop 0
	v_cvt_pk_bf16_f32 v28, v39, v37
	v_cvt_pk_bf16_f32 v29, v41, v43
	v_cvt_pk_bf16_f32 v30, v47, v49
	v_cvt_pk_bf16_f32 v31, v51, v53
	global_store_dwordx4 v[32:33], v[28:31], off sc1
	s_waitcnt lgkmcnt(0)
	s_mov_b64 s[0:1], 0
; #define LAS __attribute__((address_space(3)))
; __device__ __forceinline__ unsigned cvt_pk_bf16(float lo, float hi) { const f32x2 v = {lo, hi}; return __builtin_bit_cast(unsigned, __builtin_convertvector(v, bf16x2_t)); }
; #define LDS_WAIT() asm volatile("s_waitcnt lgkmcnt(0)" ::: "memory")
; __device__ __forceinline__ void p0_transpose_item(const float* W, int K, int N, bf16_t* WT, int k0, int n0, int drow0, LAS float* scr, int lane) {
;     const int kk = lane >> 3, nq = (lane & 7) * 4;
;     f32x4 v[8];
; #pragma unroll
;     for (int i = 0; i < 8; ++i) v[i] = __builtin_nontemporal_load((const f32x4*)(W + (size_t)(k0 + 8 * i + kk) * N + n0 + nq));
; #pragma unroll
;     for (int i = 0; i < 8; ++i) { LAS float* d = scr + (8 * i + kk) * 33 + nq; d[0] = v[i].x; d[1] = v[i].y; d[2] = v[i].z; d[3] = v[i].w; }
;     LDS_WAIT(); asm volatile("" ::: "memory");
;     const int c = lane & 7;
; #pragma unroll
;     for (int j = 0; j < 4; ++j) { const int n = (lane >> 3) + 8 * j; const LAS float* s = scr + (8 * c) * 33 + n;
;         u32x4 o; o.x = cvt_pk_bf16(s[0 * 33], s[1 * 33]); o.y = cvt_pk_bf16(s[2 * 33], s[3 * 33]); o.z = cvt_pk_bf16(s[4 * 33], s[5 * 33]); o.w = cvt_pk_bf16(s[6 * 33], s[7 * 33]);
;         *(u32x4*)(WT + (size_t)(drow0 + n) * K + k0 + 8 * c) = o; }
;     LDS_WAIT(); asm volatile("" ::: "memory");
; }
; __device__ __forceinline__ void p0_prologue(Frame& F) {
;     ...
;             if (r < 2 * I_U) { const int jj = r / I_U; r -= jj * I_U; const int j = jj * (DEPTH - 1); const int nblk = 2 * DFF / 32, kb = r / nblk, nb = r % nblk;
;                 p0_transpose_item(F.in[I_WUP] + (size_t)j * D * 2 * DFF, D, 2 * DFF, (bf16_t*)(ws + WS_WUP) + (size_t)j * 2 * DFF * D, 64 * kb, 32 * nb, 32 * nb, scr, lane); continue; } r -= 2 * I_U;
.LBB0_32:
	s_andn2_b64 vcc, exec, s[0:1]
	s_cbranch_vccnz .LBB0_34
	s_add_i32 s0, s3, 0xfffff800
	s_cmpk_gt_u32 s0, 0x2bff
	s_cselect_b32 s1, 0xd400, 0
	s_cselect_b32 s4, 3, 0
	s_add_i32 s0, s0, s1
	s_sext_i32_i16 s1, s0
	s_mulk_i32 s1, 0xba3
	s_lshr_b32 s5, s1, 31
	s_ashr_i32 s1, s1, 20
	s_add_i32 s1, s1, s5
	s_sext_i32_i16 s5, s1
	s_mulk_i32 s1, 0x160
	s_sub_i32 s0, s0, s1
	s_mul_i32 s1, s4, 0x5800000
	s_add_u32 s38, s54, s1
	s_addc_u32 s39, s55, 0
	s_mul_i32 s4, s4, 0x2c00000
	s_sext_i32_i16 s0, s0
	s_add_u32 s40, s14, s4
	s_addc_u32 s41, s15, 0
	s_lshl_b32 s0, s0, 5
	s_ashr_i32 s1, s0, 31
	s_lshl_b32 s4, s5, 6
	s_lshl_b64 s[36:37], s[0:1], 2
	s_add_u32 s36, s38, s36
	v_add_u32_e32 v7, s4, v8
	s_addc_u32 s37, s39, s37
	v_lshl_add_u64 v[58:59], s[36:37], 0, v[0:1]
	v_add_u32_e32 v45, 32, v7
	v_add_u32_e32 v30, 8, v7
	v_add_u32_e32 v36, 16, v7
	v_add_u32_e32 v38, 24, v7
	v_mad_i64_i32 v[46:47], s[36:37], v45, s35, v[58:59]
	v_add_u32_e32 v45, 40, v7
	v_mad_i64_i32 v[28:29], s[36:37], v7, s35, v[58:59]
	v_mad_i64_i32 v[32:33], s[36:37], v30, s35, v[58:59]
	v_mad_i64_i32 v[36:37], s[36:37], v36, s35, v[58:59]
	v_mad_i64_i32 v[40:41], s[36:37], v38, s35, v[58:59]
	v_mad_i64_i32 v[50:51], s[36:37], v45, s35, v[58:59]
	global_load_dwordx4 v[28:31], v[28:29], off nt
	s_nop 0
	global_load_dwordx4 v[32:35], v[32:33], off nt
	s_nop 0
	global_load_dwordx4 v[36:39], v[36:37], off nt
	s_nop 0
	global_load_dwordx4 v[40:43], v[40:41], off nt
	s_nop 0
	global_load_dwordx4 v[46:49], v[46:47], off nt
	s_nop 0
	global_load_dwordx4 v[50:53], v[50:51], off nt
	v_add_u32_e32 v45, 48, v7
	v_mad_i64_i32 v[54:55], s[36:37], v45, s35, v[58:59]
	global_load_dwordx4 v[54:57], v[54:55], off nt
	v_add_u32_e32 v7, 56, v7
	v_mad_i64_i32 v[58:59], s[36:37], v7, s35, v[58:59]
	global_load_dwordx4 v[58:61], v[58:59], off nt
	s_ashr_i32 s5, s4, 31
	s_lshl_b64 s[4:5], s[4:5], 1
	v_add_u32_e32 v62, s0, v8
	s_add_u32 s4, s40, s4
	v_mov_b32_e32 v7, v1
	v_ashrrev_i32_e32 v63, 31, v62
	s_addc_u32 s5, s41, s5
	v_lshlrev_b64 v[62:63], 12, v[62:63]
	v_lshl_add_u64 v[66:67], s[4:5], 0, v[6:7]
	v_add_u32_e32 v64, s0, v9
	v_lshl_add_u64 v[62:63], v[66:67], 0, v[62:63]
	v_ashrrev_i32_e32 v65, 31, v64
	v_lshlrev_b64 v[64:65], 12, v[64:65]
	v_lshl_add_u64 v[64:65], v[66:67], 0, v[64:65]
	s_waitcnt vmcnt(7)
	ds_write2_b32 v13, v28, v29 offset1:1
	ds_write2_b32 v13, v30, v31 offset0:2 offset1:3
	s_waitcnt vmcnt(6)
	ds_write2_b32 v14, v32, v33 offset1:1
	ds_write2_b32 v15, v34, v35 offset1:1
	s_waitcnt vmcnt(5)
	ds_write2_b32 v16, v36, v37 offset1:1
	ds_write2_b32 v17, v38, v39 offset1:1
	s_waitcnt vmcnt(4)
	ds_write2_b32 v18, v40, v41 offset1:1
	ds_write2_b32 v19, v42, v43 offset1:1
	s_waitcnt vmcnt(3)
	ds_write2_b32 v20, v46, v47 offset1:1
	ds_write2_b32 v21, v48, v49 offset1:1
	s_waitcnt vmcnt(2)
	ds_write2_b32 v22, v50, v51 offset1:1
	ds_write2_b32 v23, v52, v53 offset1:1
	s_waitcnt vmcnt(1)
	ds_write2_b32 v24, v54, v55 offset1:1
	ds_write2_b32 v25, v56, v57 offset1:1
	s_waitcnt vmcnt(0)
	ds_write2_b32 v26, v58, v59 offset1:1
	ds_write2_b32 v27, v60, v61 offset1:1
	s_waitcnt lgkmcnt(0)
	ds_read2_b32 v[32:33], v12 offset0:33 offset1:41
	ds_read2_b32 v[34:35], v12 offset1:8
	ds_read2_b32 v[36:37], v12 offset0:66 offset1:74
	ds_read2_b32 v[38:39], v12 offset0:99 offset1:107
	ds_read2_b32 v[40:41], v12 offset0:132 offset1:140
	ds_read2_b32 v[42:43], v12 offset0:165 offset1:173
	ds_read2_b32 v[46:47], v12 offset0:198 offset1:206
	ds_read2_b32 v[48:49], v12 offset0:231 offset1:239
	ds_read2_b32 v[50:51], v12 offset0:49 offset1:57
	ds_read2_b32 v[52:53], v12 offset0:16 offset1:24
	s_waitcnt lgkmcnt(8)
	v_cvt_pk_bf16_f32 v28, v34, v32
	s_waitcnt lgkmcnt(6)
	v_cvt_pk_bf16_f32 v29, v36, v38
	s_waitcnt lgkmcnt(4)
	v_cvt_pk_bf16_f32 v30, v40, v42
	s_waitcnt lgkmcnt(2)
	v_cvt_pk_bf16_f32 v31, v46, v48
	global_store_dwordx4 v[62:63], v[28:31], off sc1
	v_cvt_pk_bf16_f32 v32, v35, v33
	v_cvt_pk_bf16_f32 v33, v37, v39
	v_cvt_pk_bf16_f32 v34, v41, v43
	v_cvt_pk_bf16_f32 v35, v47, v49
	ds_read2_b32 v[36:37], v12 offset0:82 offset1:90
	ds_read2_b32 v[38:39], v12 offset0:115 offset1:123
	ds_read2_b32 v[40:41], v12 offset0:148 offset1:156
	ds_read2_b32 v[42:43], v12 offset0:181 offset1:189
	ds_read2_b32 v[46:47], v12 offset0:214 offset1:222
	ds_read2_b32 v[48:49], v12 offset0:247 offset1:255
	global_store_dwordx4 v[64:65], v[32:35], off sc1
	s_waitcnt lgkmcnt(6)
	v_cvt_pk_bf16_f32 v28, v52, v50
	s_waitcnt lgkmcnt(4)
	v_cvt_pk_bf16_f32 v29, v36, v38
	v_add_u32_e32 v32, s0, v10
	v_ashrrev_i32_e32 v33, 31, v32
	v_lshlrev_b64 v[32:33], 12, v[32:33]
	s_waitcnt lgkmcnt(2)
	v_cvt_pk_bf16_f32 v30, v40, v42
	s_waitcnt lgkmcnt(0)
	v_cvt_pk_bf16_f32 v31, v46, v48
	v_lshl_add_u64 v[32:33], v[66:67], 0, v[32:33]
	global_store_dwordx4 v[32:33], v[28:31], off sc1
	v_add_u32_e32 v32, s0, v11
	v_ashrrev_i32_e32 v33, 31, v32
	v_lshlrev_b64 v[32:33], 12, v[32:33]
	v_cvt_pk_bf16_f32 v28, v53, v51
	v_cvt_pk_bf16_f32 v29, v37, v39
	v_cvt_pk_bf16_f32 v30, v41, v43
	v_cvt_pk_bf16_f32 v31, v47, v49
	v_lshl_add_u64 v[32:33], v[66:67], 0, v[32:33]
	global_store_dwordx4 v[32:33], v[28:31], off sc1
	s_waitcnt lgkmcnt(0)

; #define LAS __attribute__((address_space(3)))
; __device__ __forceinline__ unsigned cvt_pk_bf16(float lo, float hi) { const f32x2 v = {lo, hi}; return __builtin_bit_cast(unsigned, __builtin_convertvector(v, bf16x2_t)); }
; #define LDS_WAIT() asm volatile("s_waitcnt lgkmcnt(0)" ::: "memory")
; __device__ __forceinline__ void p0_transpose_item(const float* W, int K, int N, bf16_t* WT, int k0, int n0, int drow0, LAS float* scr, int lane) {
;     const int kk = lane >> 3, nq = (lane & 7) * 4;
;     f32x4 v[8];
; #pragma unroll
;     for (int i = 0; i < 8; ++i) v[i] = __builtin_nontemporal_load((const f32x4*)(W + (size_t)(k0 + 8 * i + kk) * N + n0 + nq));
; #pragma unroll
;     for (int i = 0; i < 8; ++i) { LAS float* d = scr + (8 * i + kk) * 33 + nq; d[0] = v[i].x; d[1] = v[i].y; d[2] = v[i].z; d[3] = v[i].w; }
;     LDS_WAIT(); asm volatile("" ::: "memory");
;     const int c = lane & 7;
; #pragma unroll
;     for (int j = 0; j < 4; ++j) { const int n = (lane >> 3) + 8 * j; const LAS float* s = scr + (8 * c) * 33 + n;
;         u32x4 o; o.x = cvt_pk_bf16(s[0 * 33], s[1 * 33]); o.y = cvt_pk_bf16(s[2 * 33], s[3 * 33]); o.z = cvt_pk_bf16(s[4 * 33], s[5 * 33]); o.w = cvt_pk_bf16(s[6 * 33], s[7 * 33]);
;         *(u32x4*)(WT + (size_t)(drow0 + n) * K + k0 + 8 * c) = o; }
;     LDS_WAIT(); asm volatile("" ::: "memory");
; }
; __device__ __forceinline__ void p0_prologue(Frame& F) {
;     ...
;             if (r < I_F) { const int nblk = D / 32, kb = r / nblk, nb = r % nblk;
;                 p0_transpose_item(F.in[I_FOURW], D, D, (bf16_t*)(ws + WS_WFOUR), 64 * kb, 32 * nb, 32 * nb, scr, lane); continue; } r -= I_F;
.LBB0_35:
	s_ashr_i32 s0, s3, 31
	s_lshr_b32 s0, s0, 26
	s_add_i32 s0, s3, s0
	s_and_b32 s4, s0, 0xffffffc0
	s_lshl_b32 s0, s0, 5
	s_and_b32 s0, s0, 0xfffff800
	v_add_u32_e32 v58, s4, v8
	s_sub_i32 s0, s16, s0
	v_add_u32_e32 v30, 8, v58
	v_add_u32_e32 v36, 16, v58
	v_add_u32_e32 v38, 24, v58
	v_add_u32_e32 v46, 32, v58
	v_add_u32_e32 v48, 40, v58
	s_ashr_i32 s1, s0, 31
	v_ashrrev_i32_e32 v59, 31, v58
	v_ashrrev_i32_e32 v31, 31, v30
	v_ashrrev_i32_e32 v37, 31, v36
	v_ashrrev_i32_e32 v39, 31, v38
	v_ashrrev_i32_e32 v47, 31, v46
	v_ashrrev_i32_e32 v49, 31, v48
	v_lshl_add_u64 v[60:61], s[0:1], 2, v[4:5]
	v_lshlrev_b64 v[28:29], 13, v[58:59]
	v_lshlrev_b64 v[30:31], 13, v[30:31]
	v_lshlrev_b64 v[36:37], 13, v[36:37]
	v_lshlrev_b64 v[38:39], 13, v[38:39]
	v_lshlrev_b64 v[46:47], 13, v[46:47]
	v_lshlrev_b64 v[48:49], 13, v[48:49]
	v_lshl_add_u64 v[28:29], v[60:61], 0, v[28:29]
	v_lshl_add_u64 v[32:33], v[60:61], 0, v[30:31]
	v_lshl_add_u64 v[36:37], v[60:61], 0, v[36:37]
	v_lshl_add_u64 v[40:41], v[60:61], 0, v[38:39]
	v_lshl_add_u64 v[46:47], v[60:61], 0, v[46:47]
	v_lshl_add_u64 v[50:51], v[60:61], 0, v[48:49]
	global_load_dwordx4 v[28:31], v[28:29], off nt
	s_nop 0
	global_load_dwordx4 v[32:35], v[32:33], off nt
	s_nop 0
	global_load_dwordx4 v[36:39], v[36:37], off nt
	s_nop 0
	global_load_dwordx4 v[40:43], v[40:41], off nt
	s_nop 0
	global_load_dwordx4 v[46:49], v[46:47], off nt
	s_nop 0
	global_load_dwordx4 v[50:53], v[50:51], off nt
	v_add_u32_e32 v54, 48, v58
	v_ashrrev_i32_e32 v55, 31, v54
	v_lshlrev_b64 v[54:55], 13, v[54:55]
	v_add_u32_e32 v58, 56, v58
	v_lshl_add_u64 v[54:55], v[60:61], 0, v[54:55]
	v_ashrrev_i32_e32 v59, 31, v58
	global_load_dwordx4 v[54:57], v[54:55], off nt
	v_lshlrev_b64 v[58:59], 13, v[58:59]
	v_lshl_add_u64 v[58:59], v[60:61], 0, v[58:59]
	global_load_dwordx4 v[58:61], v[58:59], off nt
	v_add_u32_e32 v64, s0, v8
	s_ashr_i32 s5, s4, 31
	v_ashrrev_i32_e32 v65, 31, v64
	v_lshl_add_u64 v[62:63], s[4:5], 1, v[2:3]
	v_lshlrev_b64 v[68:69], 12, v[64:65]
	v_add_u32_e32 v66, 8, v64
	v_lshl_add_u64 v[68:69], v[62:63], 0, v[68:69]
	v_ashrrev_i32_e32 v67, 31, v66
	v_lshlrev_b64 v[66:67], 12, v[66:67]
	v_lshl_add_u64 v[66:67], v[62:63], 0, v[66:67]
	s_waitcnt vmcnt(7)
	ds_write2_b32 v13, v28, v29 offset1:1
	ds_write2_b32 v13, v30, v31 offset0:2 offset1:3
	s_waitcnt vmcnt(6)
	ds_write2_b32 v14, v32, v33 offset1:1
	ds_write2_b32 v15, v34, v35 offset1:1
	s_waitcnt vmcnt(5)
	ds_write2_b32 v16, v36, v37 offset1:1
	ds_write2_b32 v17, v38, v39 offset1:1
	s_waitcnt vmcnt(4)
	ds_write2_b32 v18, v40, v41 offset1:1
	ds_write2_b32 v19, v42, v43 offset1:1
	s_waitcnt vmcnt(3)
	ds_write2_b32 v20, v46, v47 offset1:1
	ds_write2_b32 v21, v48, v49 offset1:1
	s_waitcnt vmcnt(2)
	ds_write2_b32 v22, v50, v51 offset1:1
	ds_write2_b32 v23, v52, v53 offset1:1
	s_waitcnt vmcnt(1)
	ds_write2_b32 v24, v54, v55 offset1:1
	ds_write2_b32 v25, v56, v57 offset1:1
	s_waitcnt vmcnt(0)
	ds_write2_b32 v26, v58, v59 offset1:1
	ds_write2_b32 v27, v60, v61 offset1:1
	s_waitcnt lgkmcnt(0)
	ds_read2_b32 v[32:33], v12 offset0:33 offset1:41
	ds_read2_b32 v[34:35], v12 offset1:8
	ds_read2_b32 v[36:37], v12 offset0:66 offset1:74
	ds_read2_b32 v[38:39], v12 offset0:99 offset1:107
	ds_read2_b32 v[40:41], v12 offset0:132 offset1:140
	ds_read2_b32 v[42:43], v12 offset0:165 offset1:173
	ds_read2_b32 v[46:47], v12 offset0:198 offset1:206
	ds_read2_b32 v[48:49], v12 offset0:231 offset1:239
	ds_read2_b32 v[50:51], v12 offset0:49 offset1:57
	ds_read2_b32 v[52:53], v12 offset0:16 offset1:24
	ds_read2_b32 v[54:55], v12 offset0:82 offset1:90
	ds_read2_b32 v[56:57], v12 offset0:115 offset1:123
	ds_read2_b32 v[58:59], v12 offset0:148 offset1:156
	s_waitcnt lgkmcnt(11)
	v_cvt_pk_bf16_f32 v28, v34, v32
	s_waitcnt lgkmcnt(9)
	v_cvt_pk_bf16_f32 v29, v36, v38
	s_waitcnt lgkmcnt(7)
	v_cvt_pk_bf16_f32 v30, v40, v42
	s_waitcnt lgkmcnt(5)
	v_cvt_pk_bf16_f32 v31, v46, v48
	global_store_dwordx4 v[68:69], v[28:31], off sc1
	v_cvt_pk_bf16_f32 v32, v35, v33
	v_cvt_pk_bf16_f32 v33, v37, v39
	v_cvt_pk_bf16_f32 v34, v41, v43
	ds_read2_b32 v[36:37], v12 offset0:181 offset1:189
	ds_read2_b32 v[38:39], v12 offset0:214 offset1:222
	ds_read2_b32 v[40:41], v12 offset0:247 offset1:255
	v_cvt_pk_bf16_f32 v35, v47, v49
	global_store_dwordx4 v[66:67], v[32:35], off sc1
	s_waitcnt lgkmcnt(6)
	v_cvt_pk_bf16_f32 v28, v52, v50
	s_waitcnt lgkmcnt(4)
	v_cvt_pk_bf16_f32 v29, v54, v56
	v_add_u32_e32 v32, 16, v64
	v_ashrrev_i32_e32 v33, 31, v32
	v_lshlrev_b64 v[32:33], 12, v[32:33]
	s_waitcnt lgkmcnt(2)
	v_cvt_pk_bf16_f32 v30, v58, v36
	s_waitcnt lgkmcnt(0)
	v_cvt_pk_bf16_f32 v31, v38, v40
	v_lshl_add_u64 v[32:33], v[62:63], 0, v[32:33]
	global_store_dwordx4 v[32:33], v[28:31], off sc1
	v_add_u32_e32 v32, 24, v64
	v_ashrrev_i32_e32 v33, 31, v32
	v_lshlrev_b64 v[32:33], 12, v[32:33]
	v_cvt_pk_bf16_f32 v28, v53, v51
	v_cvt_pk_bf16_f32 v29, v55, v57
	v_cvt_pk_bf16_f32 v30, v59, v37
	v_cvt_pk_bf16_f32 v31, v39, v41
	v_lshl_add_u64 v[32:33], v[62:63], 0, v[32:33]
	global_store_dwordx4 v[32:33], v[28:31], off sc1
	s_waitcnt lgkmcnt(0)
	s_branch .LBB0_27

; __device__ __forceinline__ unsigned cvt_pk_bf16(float lo, float hi) { const f32x2 v = {lo, hi}; return __builtin_bit_cast(unsigned, __builtin_convertvector(v, bf16x2_t)); }
;     __device__ __forceinline__ const char* a(const pg8::Unit& u) const { return (const char*)ws + aoff + (size_t)u.pm * 256 * K_ * 2 + (u.kq < 0 ? 0 : u.kq * (K_ / 4) * 2); }
;     __device__ __forceinline__ const char* a(const pg8::Unit& u) const { return (const char*)ws + WS_A + (size_t)u.pm * 256 * D * 2; }
;     __device__ __forceinline__ const char* a(const pg8::Unit& u) const { return (const char*)ws + WS_A + (size_t)u.pm * 256 * D * 2; }
;     __device__ __forceinline__ const char* a(const pg8::Unit& u) const { return (const char*)ws + WS_W1 + (size_t)(u.pm & 1) * 256 * 256 * 2; }
;     __device__ __forceinline__ const char* a(const pg8::Unit& u) const { return (const char*)ws + (u.pm < 64 ? WS_W2 : WS_W2C); }
; __device__ __forceinline__ void p0_prologue(Frame& F) {
;     ...
;     for (size_t i = gt; i < (size_t)2 * 128 * D / 8; i += NT) { const size_t j = i / (128 * D / 8), e = i % (128 * D / 8);
;         *(u32x4*)((bf16_t*)(ws + WS_WIN) + ((size_t)j * INP + INW) * D + e * 8) = (u32x4){0u, 0u, 0u, 0u}; }
;     {
;         bf16_t* W1 = (bf16_t*)(ws + WS_W1);
;         for (size_t i = gt; i < (size_t)512 * 256 / 2; i += NT) { const int m = (int)(i / 128), c0 = (int)(i % 128) * 2; float v[2];
; #pragma unroll
;             for (int e = 0; e < 2; ++e) { const int idx = ((m & 255) * (c0 + e)) & 255; const float a = (float)idx * (1.0f / 128.0f); v[e] = (m < 256) ? cospif(a) : sinpif(a); }
;             *(unsigned*)(W1 + (size_t)m * 256 + c0) = cvt_pk_bf16(v[0], v[1]); }
.LBB0_38:
	v_lshrrev_b32_e32 v4, 15, v6
	v_and_b32_e32 v14, 0x3fff8, v2
	v_lshl_add_u64 v[6:7], v[6:7], 0, s[14:15]
	v_mul_lo_u32 v4, v4, s3
	v_cmp_lt_u64_e32 vcc, s[26:27], v[6:7]
	v_lshl_add_u64 v[12:13], s[0:1], 0, v[4:5]
	v_lshlrev_b32_e32 v4, 1, v14
	v_lshl_add_u64 v[2:3], v[2:3], 0, s[16:17]
	s_or_b64 s[4:5], vcc, s[4:5]
	v_lshl_add_u64 v[12:13], v[12:13], 0, v[4:5]
	global_store_dwordx4 v[12:13], v[8:11], off sc1
	s_andn2_b64 exec, exec, s[4:5]
	s_cbranch_execnz .LBB0_38
	s_or_b64 exec, exec, s[4:5]
	s_add_u32 s4, s66, 0x300000
	s_addc_u32 s5, s67, 0
	s_lshl_b32 s0, s2, 9
	s_add_i32 s0, s33, s0
	v_add_lshl_u32 v6, s0, v44, 1
	s_lshl_b32 s3, s90, 10
	s_mov_b64 s[16:17], 0
	s_mov_b64 s[26:27], 0x7fff
	s_mov_b32 s7, 0x7f800000
	v_mov_b32_e32 v7, 0xbf1f24be
	v_mov_b32_e32 v8, 0x3e642e9d
	s_brev_b32 s34, 1
	v_mov_b32_e32 v9, 0x7fc00000
	v_mov_b32_e32 v3, 0
	s_mov_b64 s[28:29], 0xffff
	v_mov_b32_e32 v10, v6
	v_mov_b64_e32 v[4:5], v[0:1]
	s_branch .LBB0_41
.LBB0_40:
	s_or_b64 exec, exec, s[0:1]
	v_cmp_lg_f32_e32 vcc, s7, v2
	v_lshrrev_b64 v[14:15], 7, v[4:5]
	v_and_b32_e32 v16, 0xfe, v10
	v_cndmask_b32_e32 v2, v9, v11, vcc
	v_cmp_lg_f32_e32 vcc, s7, v12
	v_lshlrev_b64 v[12:13], 9, v[14:15]
	v_lshl_add_u64 v[4:5], v[4:5], 0, s[14:15]
	v_cndmask_b32_e32 v11, v9, v17, vcc
	v_cvt_pk_bf16_f32 v11, v2, v11
	v_lshl_add_u64 v[12:13], s[4:5], 0, v[12:13]
	v_lshlrev_b32_e32 v2, 1, v16
	v_cmp_lt_u64_e32 vcc, s[28:29], v[4:5]
	v_lshl_add_u64 v[12:13], v[12:13], 0, v[2:3]
	s_or_b64 s[16:17], vcc, s[16:17]
	v_add_u32_e32 v10, s3, v10
	global_store_dword v[12:13], v11, off sc1
	s_andn2_b64 exec, exec, s[16:17]
	s_cbranch_execz .LBB0_49

; __device__ __forceinline__ unsigned cvt_pk_bf16(float lo, float hi) { const f32x2 v = {lo, hi}; return __builtin_bit_cast(unsigned, __builtin_convertvector(v, bf16x2_t)); }
;     __device__ __forceinline__ const char* a(const pg8::Unit& u) const { return (const char*)ws + aoff + (size_t)u.pm * 256 * K_ * 2 + (u.kq < 0 ? 0 : u.kq * (K_ / 4) * 2); }
;     __device__ __forceinline__ const char* a(const pg8::Unit& u) const { return (const char*)ws + WS_A + (size_t)u.pm * 256 * D * 2; }
;     __device__ __forceinline__ const char* a(const pg8::Unit& u) const { return (const char*)ws + WS_A + (size_t)u.pm * 256 * D * 2; }
;     __device__ __forceinline__ const char* a(const pg8::Unit& u) const { return (const char*)ws + WS_W1 + (size_t)(u.pm & 1) * 256 * 256 * 2; }
;     __device__ __forceinline__ const char* a(const pg8::Unit& u) const { return (const char*)ws + (u.pm < 64 ? WS_W2 : WS_W2C); }
; __device__ __forceinline__ void p0_prologue(Frame& F) {
;     ...
;         for (size_t i = gt; i < (size_t)256 * 512 / 2; i += NT) { const int k1 = (int)(i / 256), c0 = (int)(i % 256) * 2; float v[2];
; #pragma unroll
;             for (int e = 0; e < 2; ++e) { const int cc = c0 + e, l = cc & 255; const int idx = (k1 * l) & 255; const float a = (float)idx * (1.0f / 128.0f); v[e] = ((cc < 256) ? cospif(a) : -sinpif(a)) * (1.0f / 256.0f); }
;             *(unsigned*)(W2c + (size_t)k1 * 512 + c0) = cvt_pk_bf16(v[0], v[1]); }
.LBB0_50:
	s_or_b64 exec, exec, s[4:5]
	v_lshrrev_b64 v[14:15], 8, v[4:5]
	v_mul_f32_e32 v12, 0x3b800000, v12
	v_mul_f32_e32 v13, 0x3b800000, v18
	v_cvt_pk_bf16_f32 v16, v12, v13
	v_lshlrev_b64 v[12:13], 10, v[14:15]
	v_lshl_add_u64 v[4:5], v[4:5], 0, s[14:15]
	v_lshl_add_u64 v[12:13], s[16:17], 0, v[12:13]
	v_lshlrev_b32_e32 v2, 1, v2
	v_cmp_lt_u64_e32 vcc, s[28:29], v[4:5]
	v_lshl_add_u64 v[12:13], v[12:13], 0, v[2:3]
	s_or_b64 s[26:27], vcc, s[26:27]
	v_add_u32_e32 v11, s3, v11
	global_store_dword v[12:13], v16, off sc1
	s_andn2_b64 exec, exec, s[26:27]
	s_cbranch_execz .LBB0_59

; __device__ __forceinline__ unsigned cvt_pk_bf16(float lo, float hi) { const f32x2 v = {lo, hi}; return __builtin_bit_cast(unsigned, __builtin_convertvector(v, bf16x2_t)); }
;     __device__ __forceinline__ const char* a(const pg8::Unit& u) const { return (const char*)ws + aoff + (size_t)u.pm * 256 * K_ * 2 + (u.kq < 0 ? 0 : u.kq * (K_ / 4) * 2); }
;     __device__ __forceinline__ const char* a(const pg8::Unit& u) const { return (const char*)ws + WS_A + (size_t)u.pm * 256 * D * 2; }
;     __device__ __forceinline__ const char* a(const pg8::Unit& u) const { return (const char*)ws + WS_A + (size_t)u.pm * 256 * D * 2; }
;     __device__ __forceinline__ const char* a(const pg8::Unit& u) const { return (const char*)ws + WS_W1 + (size_t)(u.pm & 1) * 256 * 256 * 2; }
;     __device__ __forceinline__ const char* a(const pg8::Unit& u) const { return (const char*)ws + (u.pm < 64 ? WS_W2 : WS_W2C); }
; __device__ __forceinline__ void p0_prologue(Frame& F) {
;     ...
;         for (size_t i = gt; i < (size_t)256 * 512 / 2; i += NT) { const int k2 = (int)(i / 256), c0 = (int)(i % 256) * 2; float v[2];
; #pragma unroll
;             for (int e = 0; e < 2; ++e) { const int cc = c0 + e, l = cc & 255; const int idx = (k2 * l) & 255; const float a = (float)idx * (1.0f / 128.0f); v[e] = ((cc < 256) ? cospif(a) : sinpif(a)) * sc; }
;             *(unsigned*)(W2 + (size_t)k2 * 512 + c0) = cvt_pk_bf16(v[0], v[1]); }
.LBB0_60:
	s_or_b64 exec, exec, s[0:1]
	v_mul_f32_e32 v9, 0x3ab504f3, v9
	v_cmp_lg_f32_e32 vcc, s30, v8
	v_lshrrev_b64 v[12:13], 8, v[0:1]
	v_lshl_add_u64 v[0:1], v[0:1], 0, s[14:15]
	v_cndmask_b32_e32 v8, v7, v9, vcc
	v_mul_f32_e32 v9, 0x3ab504f3, v15
	v_cmp_lg_f32_e32 vcc, s30, v10
	v_lshlrev_b32_e32 v2, 1, v2
	v_add_u32_e32 v6, s3, v6
	v_cndmask_b32_e32 v9, v7, v9, vcc
	v_cvt_pk_bf16_f32 v10, v8, v9
	v_lshlrev_b64 v[8:9], 10, v[12:13]
	v_lshl_add_u64 v[8:9], s[4:5], 0, v[8:9]
	v_cmp_lt_u64_e32 vcc, s[26:27], v[0:1]
	v_lshl_add_u64 v[8:9], v[8:9], 0, v[2:3]
	s_or_b64 s[16:17], vcc, s[16:17]
	global_store_dword v[8:9], v10, off sc1
	s_andn2_b64 exec, exec, s[16:17]
	s_cbranch_execz .LBB0_69

; __device__ __forceinline__ void p0b_modreduce(Frame& F) {
;     ...
;     for (size_t i = gt; i < PER / 4; i += NT) { const size_t e = i * 4; const int n = (int)(e % MODW), L = (int)(e / ((size_t)9 * MODW));
;         f32x4 s = *(const f32x4*)(bm + (size_t)L * MODW + n);
; #pragma unroll
;         for (int ks = 0; ks < 8; ++ks) s += *(const f32x4*)(modp + (size_t)ks * PER + e);
;         *(f32x4*)(mod + e) = s; }
.LBB0_126:
	v_add_co_u32_e32 v12, vcc, s29, v2
	v_mul_hi_u32 v4, v6, s7
	s_nop 0
	v_addc_co_u32_e32 v13, vcc, 0, v3, vcc
	v_add_co_u32_e32 v16, vcc, s30, v2
	v_lshrrev_b32_e32 v7, 10, v0
	s_nop 0
	v_addc_co_u32_e32 v17, vcc, 0, v3, vcc
	v_add_co_u32_e32 v20, vcc, s31, v2
	v_lshrrev_b32_e32 v4, 13, v4
	s_nop 0
	v_addc_co_u32_e32 v21, vcc, 0, v3, vcc
	v_add_co_u32_e32 v24, vcc, s34, v2
	v_mul_hi_u32 v7, v7, s28
	s_nop 0
	v_addc_co_u32_e32 v25, vcc, 0, v3, vcc
	v_add_co_u32_e32 v32, vcc, s35, v2
	v_mul_u32_u24_e32 v28, 0x3000, v4
	s_nop 0
	v_addc_co_u32_e32 v33, vcc, 0, v3, vcc
	v_mul_u32_u24_e32 v4, 0xc000, v7
	v_sub_u32_e32 v7, v6, v28
	global_load_dwordx4 v[8:11], v[2:3], off
	v_add_co_u32_e32 v36, vcc, s36, v2
	v_lshl_add_u64 v[28:29], s[18:19], 0, v[4:5]
	v_lshlrev_b32_e32 v4, 2, v7
	v_addc_co_u32_e32 v37, vcc, 0, v3, vcc
	v_lshl_add_u64 v[28:29], v[28:29], 0, v[4:5]
	global_load_dwordx4 v[12:15], v[12:13], off
	s_nop 0
	global_load_dwordx4 v[16:19], v[16:17], off
	s_nop 0
	global_load_dwordx4 v[20:23], v[20:21], off
	s_nop 0
	global_load_dwordx4 v[24:27], v[24:25], off
	s_nop 0
	global_load_dwordx4 v[28:31], v[28:29], off
	s_nop 0
	global_load_dwordx4 v[32:35], v[32:33], off
	s_nop 0
	global_load_dwordx4 v[36:39], v[36:37], off
	v_add_co_u32_e32 v40, vcc, s37, v2
	v_lshl_add_u64 v[0:1], v[0:1], 0, s[10:11]
	s_nop 0
	v_addc_co_u32_e32 v41, vcc, 0, v3, vcc
	global_load_dwordx4 v[40:43], v[40:41], off
	v_cmp_lt_u64_e64 s[0:1], s[26:27], v[0:1]
	v_add_co_u32_e32 v44, vcc, 0xe0b00000, v2
	s_or_b64 s[16:17], s[0:1], s[16:17]
	s_nop 0
	v_addc_co_u32_e32 v45, vcc, -1, v3, vcc
	v_lshl_add_u64 v[2:3], v[2:3], 0, s[14:15]
	v_add_u32_e32 v6, s3, v6
	s_waitcnt vmcnt(3)
	v_pk_add_f32 v[10:11], v[30:31], v[10:11]
	v_pk_add_f32 v[8:9], v[28:29], v[8:9]
	v_pk_add_f32 v[10:11], v[10:11], v[14:15]
	v_pk_add_f32 v[8:9], v[8:9], v[12:13]
	v_pk_add_f32 v[10:11], v[10:11], v[18:19]
	v_pk_add_f32 v[8:9], v[8:9], v[16:17]
	v_pk_add_f32 v[10:11], v[10:11], v[22:23]
	v_pk_add_f32 v[8:9], v[8:9], v[20:21]
	v_pk_add_f32 v[10:11], v[10:11], v[26:27]
	v_pk_add_f32 v[8:9], v[8:9], v[24:25]
	s_waitcnt vmcnt(2)
	v_pk_add_f32 v[10:11], v[10:11], v[34:35]
	v_pk_add_f32 v[8:9], v[8:9], v[32:33]
	s_waitcnt vmcnt(1)
	v_pk_add_f32 v[10:11], v[10:11], v[38:39]
	v_pk_add_f32 v[8:9], v[8:9], v[36:37]
	s_waitcnt vmcnt(0)
	v_pk_add_f32 v[10:11], v[10:11], v[42:43]
	v_pk_add_f32 v[8:9], v[8:9], v[40:41]
	global_store_dwordx4 v[44:45], v[8:11], off sc1
	s_andn2_b64 exec, exec, s[16:17]
	s_cbranch_execnz .LBB0_126

; __device__ __forceinline__ float bf_lo(unsigned u) { return __uint_as_float(u << 16); }
; __device__ __forceinline__ float bf_hi(unsigned u) { return __uint_as_float(u & 0xffff0000u); }
;     __device__ __forceinline__ const char* b(const pg8::Unit& u) const { return (const char*)ws + boff + (size_t)u.pn * 256 * K_ * 2 + (u.kq < 0 ? 0 : u.kq * (K_ / 4) * 2); }
;     __device__ __forceinline__ const char* b(const pg8::Unit& u) const { return (const char*)ws + boff + (size_t)u.pn * 256 * D * 2; }
;     __device__ __forceinline__ const char* b(const pg8::Unit& u) const { return (const char*)ws + boff + (size_t)u.pn * 256 * D * 2; }
; __device__ __forceinline__ void fft8_phase(Frame& F) {
;     ...
;         const bf16_t* src = pqt + (size_t)row * 4096 + 4 * lane;
;         u32x2 rp[8], rq[8];
; #pragma unroll
;         for (int l1 = 0; l1 < 8; ++l1) { rp[l1] = __builtin_nontemporal_load((const u32x2*)(src + 256 * l1)); rq[l1] = __builtin_nontemporal_load((const u32x2*)(src + 2048 + 256 * l1)); }
;         const int b = row >> 11, n = row & 2047;
;         bf16_t* dst = vt + (((size_t)b * 8) * 2048 + n) * 512 + 4 * lane;
;         float vr[8][4], vi[8][4];
; #pragma unroll
;         for (int e = 0; e < 4; ++e) {
;             float xr[8], xi[8];
; #pragma unroll
;             for (int l1 = 0; l1 < 8; ++l1) { const unsigned wp = (e < 2) ? rp[l1].x : rp[l1].y, wq = (e < 2) ? rq[l1].x : rq[l1].y; xr[l1] = (e & 1) ? bf_hi(wp) : bf_lo(wp); xi[l1] = -((e & 1) ? bf_hi(wq) : bf_lo(wq)); }
;             const float a0r = xr[0] + xr[4], a0i = xi[0] + xi[4], a1r = xr[0] - xr[4], a1i = xi[0] - xi[4], a2r = xr[2] + xr[6], a2i = xi[2] + xi[6], a3r = xr[2] - xr[6], a3i = xi[2] - xi[6];
;             const float a4r = xr[1] + xr[5], a4i = xi[1] + xi[5], a5r = xr[1] - xr[5], a5i = xi[1] - xi[5], a6r = xr[3] + xr[7], a6i = xi[3] + xi[7], a7r = xr[3] - xr[7], a7i = xi[3] - xi[7];
;             const float b0r = a0r + a2r, b0i = a0i + a2i, b2r = a0r - a2r, b2i = a0i - a2i, b1r = a1r + a3i, b1i = a1i - a3r, b3r = a1r - a3i, b3i = a1i + a3r;
;             const float c0r = a4r + a6r, c0i = a4i + a6i, c2r = a4r - a6r, c2i = a4i - a6i, c1r = a5r + a7i, c1i = a5i - a7r, c3r = a5r - a7i, c3i = a5i + a7r;
;             const float d1r = (c1r + c1i) * R2, d1i = (c1i - c1r) * R2, d2r = c2i, d2i = -c2r, d3r = (c3i - c3r) * R2, d3i = -(c3r + c3i) * R2;
.LBB0_808:
	v_add_co_u32_e32 v60, vcc, 0x1000, v58
	global_load_dwordx2 v[90:91], v[58:59], off nt
	s_nop 0
	v_addc_co_u32_e32 v61, vcc, 0, v59, vcc
	global_load_dwordx2 v[92:93], v[60:61], off nt
	global_load_dwordx2 v[94:95], v[58:59], off offset:512 nt
	global_load_dwordx2 v[96:97], v[60:61], off offset:512 nt
	global_load_dwordx2 v[98:99], v[58:59], off offset:1024 nt
	global_load_dwordx2 v[100:101], v[60:61], off offset:1024 nt
	global_load_dwordx2 v[88:89], v[58:59], off offset:1536 nt
	global_load_dwordx2 v[86:87], v[60:61], off offset:1536 nt
	global_load_dwordx2 v[102:103], v[58:59], off offset:2048 nt
	global_load_dwordx2 v[104:105], v[60:61], off offset:2048 nt
	global_load_dwordx2 v[106:107], v[58:59], off offset:2560 nt
	global_load_dwordx2 v[108:109], v[60:61], off offset:2560 nt
	global_load_dwordx2 v[110:111], v[58:59], off offset:3072 nt
	global_load_dwordx2 v[112:113], v[60:61], off offset:3072 nt
	global_load_dwordx2 v[114:115], v[58:59], off offset:3584 nt
	global_load_dwordx2 v[116:117], v[60:61], off offset:3584 nt
	s_ashr_i32 s0, s5, 11
	s_ashr_i32 s1, s0, 31
	s_and_b32 s6, s4, 0xffe00
	s_lshl_b64 s[0:1], s[0:1], 24
	s_add_u32 s0, s27, s0
	s_addc_u32 s1, s44, s1
	s_lshl_b32 s6, s6, 1
	s_add_u32 s0, s0, s6
	s_addc_u32 s1, s1, 0
	s_add_i32 s5, s5, s72
	s_add_i32 s4, s4, s17
	v_lshl_add_u64 v[58:59], v[58:59], 0, s[10:11]
	s_cmpk_lt_i32 s5, 0x4000
	s_waitcnt vmcnt(14)
	v_lshlrev_b32_e32 v64, 16, v92
	v_and_b32_e32 v65, 0xffff0000, v92
	s_waitcnt vmcnt(13)
	v_lshlrev_b32_e32 v76, 16, v94
	s_waitcnt vmcnt(11)
	v_lshlrev_b32_e32 v68, 16, v98
	v_and_b32_e32 v69, 0xffff0000, v98
	s_waitcnt vmcnt(10)
	v_lshlrev_b32_e32 v72, 16, v100
	v_and_b32_e32 v73, 0xffff0000, v100
	s_waitcnt vmcnt(7)
	v_lshlrev_b32_e32 v62, 16, v102
	v_and_b32_e32 v63, 0xffff0000, v102
	s_waitcnt vmcnt(6)
	v_lshlrev_b32_e32 v66, 16, v104
	v_and_b32_e32 v67, 0xffff0000, v104
	v_lshlrev_b32_e32 v60, 16, v90
	v_and_b32_e32 v61, 0xffff0000, v90
	s_waitcnt vmcnt(3)
	v_lshlrev_b32_e32 v70, 16, v110
	v_and_b32_e32 v71, 0xffff0000, v110
	s_waitcnt vmcnt(2)
	v_lshlrev_b32_e32 v74, 16, v112
	v_and_b32_e32 v75, 0xffff0000, v112
	v_and_b32_e32 v77, 0xffff0000, v94
	v_lshlrev_b32_e32 v78, 16, v106
	v_and_b32_e32 v79, 0xffff0000, v106
	v_lshlrev_b32_e32 v80, 16, v96
	v_and_b32_e32 v81, 0xffff0000, v96
	v_lshlrev_b32_e32 v82, 16, v108
	v_and_b32_e32 v83, 0xffff0000, v108
	v_lshlrev_b32_e32 v84, 16, v88
	v_and_b32_e32 v85, 0xffff0000, v88
	s_waitcnt vmcnt(1)
	v_lshlrev_b32_e32 v118, 16, v114
	v_and_b32_e32 v119, 0xffff0000, v114
	v_lshlrev_b32_e32 v120, 16, v86
	v_and_b32_e32 v121, 0xffff0000, v86
	s_waitcnt vmcnt(0)
	v_lshlrev_b32_e32 v122, 16, v116
	v_and_b32_e32 v123, 0xffff0000, v116
	v_pk_add_f32 v[124:125], v[60:61], v[62:63]
	v_pk_add_f32 v[126:127], v[68:69], v[70:71]
	v_pk_add_f32 v[128:129], v[66:67], v[64:65] neg_lo:[1,1] neg_hi:[1,1]
	v_pk_add_f32 v[130:131], v[74:75], v[72:73] neg_lo:[1,1] neg_hi:[1,1]
	v_pk_add_f32 v[132:133], v[76:77], v[78:79]
	v_pk_add_f32 v[134:135], v[84:85], v[118:119]
	v_pk_add_f32 v[136:137], v[82:83], v[80:81] neg_lo:[1,1] neg_hi:[1,1]
	v_pk_add_f32 v[138:139], v[122:123], v[120:121] neg_lo:[1,1] neg_hi:[1,1]
	v_pk_add_f32 v[60:61], v[60:61], v[62:63] neg_lo:[0,1] neg_hi:[0,1]
	v_pk_add_f32 v[62:63], v[74:75], v[72:73] neg_lo:[0,1] neg_hi:[0,1]
	v_pk_add_f32 v[64:65], v[66:67], v[64:65] neg_lo:[0,1] neg_hi:[0,1]
	v_pk_add_f32 v[66:67], v[68:69], v[70:71] neg_lo:[0,1] neg_hi:[0,1]
	v_pk_add_f32 v[68:69], v[76:77], v[78:79] neg_lo:[0,1] neg_hi:[0,1]
	v_pk_add_f32 v[70:71], v[122:123], v[120:121] neg_lo:[0,1] neg_hi:[0,1]
	v_pk_add_f32 v[72:73], v[82:83], v[80:81] neg_lo:[0,1] neg_hi:[0,1]
	v_pk_add_f32 v[74:75], v[84:85], v[118:119] neg_lo:[0,1] neg_hi:[0,1]
	v_pk_add_f32 v[140:141], v[124:125], v[126:127]
	v_pk_add_f32 v[142:143], v[132:133], v[134:135]
	v_pk_add_f32 v[144:145], v[128:129], v[130:131]
	v_pk_add_f32 v[146:147], v[136:137], v[138:139]
	v_pk_add_f32 v[118:119], v[60:61], v[62:63]
	v_pk_add_f32 v[76:77], v[68:69], v[70:71]
	v_pk_add_f32 v[60:61], v[60:61], v[62:63] neg_lo:[0,1] neg_hi:[0,1]
	v_pk_add_f32 v[62:63], v[68:69], v[70:71] neg_lo:[0,1] neg_hi:[0,1]
	v_pk_add_f32 v[68:69], v[72:73], v[74:75]
	v_pk_add_f32 v[148:149], v[140:141], v[142:143]
	v_pk_add_f32 v[150:151], v[144:145], v[146:147]
	v_pk_add_f32 v[78:79], v[72:73], v[74:75] neg_lo:[0,1] neg_hi:[0,1]
	v_pk_add_f32 v[122:123], v[64:65], v[66:67] neg_lo:[0,1] neg_hi:[0,1]
	v_pk_add_f32 v[128:129], v[128:129], v[130:131] neg_lo:[0,1] neg_hi:[0,1]
	v_pk_add_f32 v[130:131], v[132:133], v[134:135] neg_lo:[0,1] neg_hi:[0,1]
	v_pk_add_f32 v[64:65], v[64:65], v[66:67]
	v_pk_add_f32 v[134:135], v[68:69], v[62:63]
	v_pk_fma_f32 v[152:153], v[150:151], 0, v[148:149] op_sel_hi:[1,0,1]
	v_pk_fma_f32 v[148:149], v[148:149], 0, v[150:151] op_sel_hi:[1,0,1] neg_lo:[1,0,0] neg_hi:[1,0,0]
	v_pk_add_f32 v[150:151], v[78:79], v[76:77] neg_lo:[0,1] neg_hi:[0,1]
	v_pk_add_f32 v[132:133], v[68:69], v[62:63] neg_lo:[0,1] neg_hi:[0,1]
	v_pk_fma_f32 v[62:63], v[134:135], s[50:51], v[64:65] op_sel_hi:[1,0,1]
	v_pk_add_f32 v[120:121], v[78:79], v[76:77]
	v_pk_fma_f32 v[76:77], v[150:151], s[48:49], v[122:123] op_sel_hi:[1,0,1]
	v_pk_fma_f32 v[66:67], v[132:133], s[48:49], v[60:61] op_sel_hi:[1,0,1]
	v_pk_mul_f32 v[68:69], v[20:21], v[62:63]
	v_pk_fma_f32 v[78:79], v[120:121], s[48:49], v[118:119] op_sel_hi:[1,0,1]
	v_pk_mul_f32 v[80:81], v[4:5], v[76:77]
	v_pk_add_f32 v[124:125], v[124:125], v[126:127] neg_lo:[0,1] neg_hi:[0,1]
	v_pk_add_f32 v[126:127], v[136:137], v[138:139] neg_lo:[0,1] neg_hi:[0,1]
	v_pk_fma_f32 v[84:85], v[18:19], v[66:67], v[68:69]
	v_pk_mul_f32 v[66:67], v[20:21], v[66:67]
; __device__ __forceinline__ void fft8_phase(Frame& F) {
;     ...
;             const float a0r = xr[0] + xr[4], a0i = xi[0] + xi[4], a1r = xr[0] - xr[4], a1i = xi[0] - xi[4], a2r = xr[2] + xr[6], a2i = xi[2] + xi[6], a3r = xr[2] - xr[6], a3i = xi[2] - xi[6];
;             const float a4r = xr[1] + xr[5], a4i = xi[1] + xi[5], a5r = xr[1] - xr[5], a5i = xi[1] - xi[5], a6r = xr[3] + xr[7], a6i = xi[3] + xi[7], a7r = xr[3] - xr[7], a7i = xi[3] - xi[7];
;             const float b0r = a0r + a2r, b0i = a0i + a2i, b2r = a0r - a2r, b2i = a0i - a2i, b1r = a1r + a3i, b1i = a1i - a3r, b3r = a1r - a3i, b3i = a1i + a3r;
;             const float c0r = a4r + a6r, c0i = a4i + a6i, c2r = a4r - a6r, c2i = a4i - a6i, c1r = a5r + a7i, c1i = a5i - a7r, c3r = a5r - a7i, c3i = a5i + a7r;
;             const float d1r = (c1r + c1i) * R2, d1i = (c1i - c1r) * R2, d2r = c2i, d2i = -c2r, d3r = (c3i - c3r) * R2, d3i = -(c3r + c3i) * R2;
;             float yr[8], yi[8];
;             yr[0] = b0r + c0r; yi[0] = b0i + c0i; yr[4] = b0r - c0r; yi[4] = b0i - c0i;
;             yr[1] = b1r + d1r; yi[1] = b1i + d1i; yr[5] = b1r - d1r; yi[5] = b1i - d1i;
;             yr[2] = b2r + d2r; yi[2] = b2i + d2i; yr[6] = b2r - d2r; yi[6] = b2i - d2i;
;             yr[3] = b3r + d3r; yi[3] = b3i + d3i; yr[7] = b3r - d3r; yi[7] = b3i - d3i;
; #pragma unroll
;             for (int k1 = 0; k1 < 8; ++k1) { const float c = twc[k1][e], sn = tws[k1][e]; vr[k1][e] = yr[k1] * c + yi[k1] * sn; vi[k1][e] = yi[k1] * c - yr[k1] * sn; }
	v_pk_fma_f32 v[154:155], v[2:3], v[78:79], v[80:81]
	v_pk_mul_f32 v[78:79], v[4:5], v[78:79]
	v_pk_add_f32 v[80:81], v[124:125], v[126:127]
	v_pk_fma_f32 v[74:75], v[18:19], v[62:63], v[66:67] neg_lo:[0,0,1] neg_hi:[0,0,1]
	v_pk_add_f32 v[62:63], v[144:145], v[146:147] neg_lo:[0,1] neg_hi:[0,1]
	v_pk_fma_f32 v[78:79], v[2:3], v[76:77], v[78:79] neg_lo:[0,0,1] neg_hi:[0,0,1]
	v_pk_add_f32 v[76:77], v[128:129], v[130:131] neg_lo:[0,1] neg_hi:[0,1]
	v_pk_mul_f32 v[82:83], v[10:11], v[80:81]
	v_pk_mul_f32 v[80:81], v[12:13], v[80:81]
	v_pk_add_f32 v[66:67], v[140:141], v[142:143] neg_lo:[0,1] neg_hi:[0,1]
	v_pk_mul_f32 v[68:69], v[28:29], v[62:63]
	v_pk_fma_f32 v[82:83], v[12:13], v[76:77], v[82:83]
	v_pk_fma_f32 v[80:81], v[10:11], v[76:77], v[80:81] neg_lo:[0,0,1] neg_hi:[0,0,1]
	v_pk_fma_f32 v[76:77], v[26:27], v[66:67], v[68:69]
	v_pk_mul_f32 v[66:67], v[28:29], v[66:67]
	v_pk_fma_f32 v[60:61], v[132:133], s[48:49], v[60:61] op_sel_hi:[1,0,1] neg_lo:[1,0,0] neg_hi:[1,0,0]
	v_pk_fma_f32 v[70:71], v[26:27], v[62:63], v[66:67] neg_lo:[0,0,1] neg_hi:[0,0,1]
	v_pk_fma_f32 v[62:63], v[150:151], s[48:49], v[122:123] op_sel_hi:[1,0,1] neg_lo:[1,0,0] neg_hi:[1,0,0]
	v_pk_fma_f32 v[66:67], v[120:121], s[48:49], v[118:119] op_sel_hi:[1,0,1] neg_lo:[1,0,0] neg_hi:[1,0,0]
	v_pk_mul_f32 v[68:69], v[36:37], v[62:63]
	v_pk_add_f32 v[118:119], v[124:125], v[126:127] neg_lo:[0,1] neg_hi:[0,1]
	v_pk_fma_f32 v[72:73], v[34:35], v[66:67], v[68:69]
	v_pk_mul_f32 v[66:67], v[36:37], v[66:67]
	v_pk_mul_f32 v[68:69], v[42:43], v[118:119]
	v_pk_fma_f32 v[66:67], v[34:35], v[62:63], v[66:67] neg_lo:[0,0,1] neg_hi:[0,0,1]
	v_pk_add_f32 v[62:63], v[128:129], v[130:131]
	v_pk_mul_f32 v[118:119], v[44:45], v[118:119]
	v_pk_fma_f32 v[68:69], v[44:45], v[62:63], v[68:69]
	v_pk_fma_f32 v[62:63], v[42:43], v[62:63], v[118:119] neg_lo:[0,0,1] neg_hi:[0,0,1]
	v_pk_fma_f32 v[118:119], v[134:135], s[50:51], v[64:65] op_sel_hi:[1,0,1] neg_lo:[1,0,0] neg_hi:[1,0,0]
	v_lshlrev_b32_e32 v90, 16, v91
	v_pk_mul_f32 v[64:65], v[52:53], v[118:119]
	v_and_b32_e32 v91, 0xffff0000, v91
	v_pk_fma_f32 v[64:65], v[50:51], v[60:61], v[64:65]
	v_pk_mul_f32 v[60:61], v[52:53], v[60:61]
	v_lshlrev_b32_e32 v102, 16, v103
	v_and_b32_e32 v103, 0xffff0000, v103
	v_lshlrev_b32_e32 v92, 16, v93
	v_and_b32_e32 v93, 0xffff0000, v93
	v_lshlrev_b32_e32 v104, 16, v105
	v_and_b32_e32 v105, 0xffff0000, v105
	v_lshlrev_b32_e32 v98, 16, v99
	v_and_b32_e32 v99, 0xffff0000, v99
	v_lshlrev_b32_e32 v110, 16, v111
	v_and_b32_e32 v111, 0xffff0000, v111
	v_lshlrev_b32_e32 v100, 16, v101
	v_and_b32_e32 v101, 0xffff0000, v101
	v_lshlrev_b32_e32 v112, 16, v113
	v_and_b32_e32 v113, 0xffff0000, v113
	v_lshlrev_b32_e32 v94, 16, v95
	v_and_b32_e32 v95, 0xffff0000, v95
	v_lshlrev_b32_e32 v106, 16, v107
	v_and_b32_e32 v107, 0xffff0000, v107
	v_lshlrev_b32_e32 v96, 16, v97
	v_and_b32_e32 v97, 0xffff0000, v97
	v_lshlrev_b32_e32 v108, 16, v109
	v_and_b32_e32 v109, 0xffff0000, v109
	v_lshlrev_b32_e32 v88, 16, v89
	v_and_b32_e32 v89, 0xffff0000, v89
	v_lshlrev_b32_e32 v114, 16, v115
	v_and_b32_e32 v115, 0xffff0000, v115
	v_lshlrev_b32_e32 v86, 16, v87
	v_and_b32_e32 v87, 0xffff0000, v87
	v_lshlrev_b32_e32 v116, 16, v117
	v_and_b32_e32 v117, 0xffff0000, v117
	v_pk_fma_f32 v[60:61], v[50:51], v[118:119], v[60:61] neg_lo:[0,0,1] neg_hi:[0,0,1]
	v_pk_add_f32 v[118:119], v[90:91], v[102:103]
	v_pk_add_f32 v[120:121], v[98:99], v[110:111]
	v_pk_add_f32 v[122:123], v[104:105], v[92:93] neg_lo:[1,1] neg_hi:[1,1]
	v_pk_add_f32 v[124:125], v[112:113], v[100:101] neg_lo:[1,1] neg_hi:[1,1]
	v_pk_add_f32 v[126:127], v[94:95], v[106:107]
	v_pk_add_f32 v[128:129], v[88:89], v[114:115]
	v_pk_add_f32 v[130:131], v[108:109], v[96:97] neg_lo:[1,1] neg_hi:[1,1]
	v_pk_add_f32 v[132:133], v[116:117], v[86:87] neg_lo:[1,1] neg_hi:[1,1]
	v_pk_add_f32 v[134:135], v[118:119], v[120:121]
	v_pk_add_f32 v[136:137], v[126:127], v[128:129]
	v_pk_add_f32 v[138:139], v[122:123], v[124:125]
	v_pk_add_f32 v[140:141], v[130:131], v[132:133]
	v_pk_add_f32 v[94:95], v[94:95], v[106:107] neg_lo:[0,1] neg_hi:[0,1]
	v_pk_add_f32 v[86:87], v[116:117], v[86:87] neg_lo:[0,1] neg_hi:[0,1]
	v_pk_add_f32 v[96:97], v[108:109], v[96:97] neg_lo:[0,1] neg_hi:[0,1]
	v_pk_add_f32 v[88:89], v[88:89], v[114:115] neg_lo:[0,1] neg_hi:[0,1]
	v_pk_add_f32 v[142:143], v[134:135], v[136:137]
	v_pk_add_f32 v[144:145], v[138:139], v[140:141]
	v_pk_add_f32 v[90:91], v[90:91], v[102:103] neg_lo:[0,1] neg_hi:[0,1]
	v_pk_add_f32 v[92:93], v[104:105], v[92:93] neg_lo:[0,1] neg_hi:[0,1]
	v_pk_add_f32 v[98:99], v[98:99], v[110:111] neg_lo:[0,1] neg_hi:[0,1]
	v_pk_add_f32 v[102:103], v[94:95], v[86:87]
	v_pk_add_f32 v[104:105], v[96:97], v[88:89] neg_lo:[0,1] neg_hi:[0,1]
	v_pk_fma_f32 v[146:147], v[144:145], 0, v[142:143] op_sel_hi:[1,0,1]
	v_pk_fma_f32 v[142:143], v[142:143], 0, v[144:145] op_sel_hi:[1,0,1] neg_lo:[1,0,0] neg_hi:[1,0,0]
	v_pk_add_f32 v[100:101], v[112:113], v[100:101] neg_lo:[0,1] neg_hi:[0,1]
	v_pk_add_f32 v[144:145], v[92:93], v[98:99] neg_lo:[0,1] neg_hi:[0,1]
	v_pk_add_f32 v[150:151], v[104:105], v[102:103] neg_lo:[0,1] neg_hi:[0,1]
	v_pk_add_f32 v[114:115], v[90:91], v[100:101]
	v_pk_add_f32 v[116:117], v[104:105], v[102:103]
	v_pk_fma_f32 v[102:103], v[150:151], s[48:49], v[144:145] op_sel_hi:[1,0,1]
	v_pk_add_f32 v[86:87], v[94:95], v[86:87] neg_lo:[0,1] neg_hi:[0,1]
	v_pk_add_f32 v[88:89], v[96:97], v[88:89]
	v_pk_fma_f32 v[104:105], v[116:117], s[48:49], v[114:115] op_sel_hi:[1,0,1]
	v_pk_mul_f32 v[106:107], v[8:9], v[102:103]
	v_pk_add_f32 v[122:123], v[122:123], v[124:125] neg_lo:[0,1] neg_hi:[0,1]
	v_pk_add_f32 v[124:125], v[126:127], v[128:129] neg_lo:[0,1] neg_hi:[0,1]
; __device__ __forceinline__ unsigned cvt_pk_bf16(float lo, float hi) { const f32x2 v = {lo, hi}; return __builtin_bit_cast(unsigned, __builtin_convertvector(v, bf16x2_t)); }
; __device__ __forceinline__ void fft8_phase(Frame& F) {
;     ...
;             const float d1r = (c1r + c1i) * R2, d1i = (c1i - c1r) * R2, d2r = c2i, d2i = -c2r, d3r = (c3i - c3r) * R2, d3i = -(c3r + c3i) * R2;
;             float yr[8], yi[8];
;             yr[0] = b0r + c0r; yi[0] = b0i + c0i; yr[4] = b0r - c0r; yi[4] = b0i - c0i;
;             yr[1] = b1r + d1r; yi[1] = b1i + d1i; yr[5] = b1r - d1r; yi[5] = b1i - d1i;
;             yr[2] = b2r + d2r; yi[2] = b2i + d2i; yr[6] = b2r - d2r; yi[6] = b2i - d2i;
;             yr[3] = b3r + d3r; yi[3] = b3i + d3i; yr[7] = b3r - d3r; yi[7] = b3i - d3i;
; #pragma unroll
;             for (int k1 = 0; k1 < 8; ++k1) { const float c = twc[k1][e], sn = tws[k1][e]; vr[k1][e] = yr[k1] * c + yi[k1] * sn; vi[k1][e] = yi[k1] * c - yr[k1] * sn; }
;         }
; #pragma unroll
;         for (int k1 = 0; k1 < 8; ++k1) { u32x2 o; o.x = cvt_pk_bf16(vr[k1][0], vr[k1][1]); o.y = cvt_pk_bf16(vr[k1][2], vr[k1][3]); *(u32x2*)(dst + (size_t)k1 * 2048 * 512) = o;
;             u32x2 p; p.x = cvt_pk_bf16(vi[k1][0], vi[k1][1]); p.y = cvt_pk_bf16(vi[k1][2], vi[k1][3]); *(u32x2*)(dst + (size_t)k1 * 2048 * 512 + 256) = p; }
	v_pk_add_f32 v[128:129], v[88:89], v[86:87] neg_lo:[0,1] neg_hi:[0,1]
	v_pk_add_f32 v[92:93], v[92:93], v[98:99]
	v_pk_add_f32 v[86:87], v[88:89], v[86:87]
	v_pk_fma_f32 v[156:157], v[6:7], v[104:105], v[106:107]
	v_pk_mul_f32 v[104:105], v[8:9], v[104:105]
	v_pk_add_f32 v[118:119], v[118:119], v[120:121] neg_lo:[0,1] neg_hi:[0,1]
	v_pk_add_f32 v[120:121], v[130:131], v[132:133] neg_lo:[0,1] neg_hi:[0,1]
	v_pk_add_f32 v[126:127], v[90:91], v[100:101] neg_lo:[0,1] neg_hi:[0,1]
	v_pk_fma_f32 v[88:89], v[86:87], s[50:51], v[92:93] op_sel_hi:[1,0,1]
	v_pk_fma_f32 v[106:107], v[6:7], v[102:103], v[104:105] neg_lo:[0,0,1] neg_hi:[0,0,1]
	v_pk_add_f32 v[104:105], v[118:119], v[120:121]
	v_pk_fma_f32 v[90:91], v[128:129], s[48:49], v[126:127] op_sel_hi:[1,0,1]
	v_pk_mul_f32 v[94:95], v[24:25], v[88:89]
	v_pk_add_f32 v[102:103], v[122:123], v[124:125] neg_lo:[0,1] neg_hi:[0,1]
	v_pk_mul_f32 v[108:109], v[14:15], v[104:105]
	v_pk_mul_f32 v[104:105], v[16:17], v[104:105]
	v_pk_fma_f32 v[112:113], v[22:23], v[90:91], v[94:95]
	v_pk_mul_f32 v[90:91], v[24:25], v[90:91]
	v_pk_fma_f32 v[110:111], v[16:17], v[102:103], v[108:109]
	v_pk_fma_f32 v[108:109], v[14:15], v[102:103], v[104:105] neg_lo:[0,0,1] neg_hi:[0,0,1]
	v_pk_fma_f32 v[102:103], v[22:23], v[88:89], v[90:91] neg_lo:[0,0,1] neg_hi:[0,0,1]
	v_pk_add_f32 v[88:89], v[138:139], v[140:141] neg_lo:[0,1] neg_hi:[0,1]
	v_pk_add_f32 v[90:91], v[134:135], v[136:137] neg_lo:[0,1] neg_hi:[0,1]
	v_pk_mul_f32 v[94:95], v[32:33], v[88:89]
	v_pk_fma_f32 v[86:87], v[86:87], s[50:51], v[92:93] op_sel_hi:[1,0,1] neg_lo:[1,0,0] neg_hi:[1,0,0]
	v_pk_fma_f32 v[104:105], v[30:31], v[90:91], v[94:95]
	v_pk_mul_f32 v[90:91], v[32:33], v[90:91]
	v_pk_mul_f32 v[92:93], v[56:57], v[86:87]
	v_pk_fma_f32 v[98:99], v[30:31], v[88:89], v[90:91] neg_lo:[0,0,1] neg_hi:[0,0,1]
	v_pk_fma_f32 v[88:89], v[150:151], s[48:49], v[144:145] op_sel_hi:[1,0,1] neg_lo:[1,0,0] neg_hi:[1,0,0]
	v_pk_fma_f32 v[90:91], v[116:117], s[48:49], v[114:115] op_sel_hi:[1,0,1] neg_lo:[1,0,0] neg_hi:[1,0,0]
	v_pk_mul_f32 v[94:95], v[40:41], v[88:89]
	v_cvt_pk_bf16_f32 v78, v78, v79
	v_pk_fma_f32 v[100:101], v[38:39], v[90:91], v[94:95]
	v_pk_mul_f32 v[90:91], v[40:41], v[90:91]
	v_cvt_pk_bf16_f32 v79, v106, v107
	v_pk_fma_f32 v[94:95], v[38:39], v[88:89], v[90:91] neg_lo:[0,0,1] neg_hi:[0,0,1]
	v_pk_add_f32 v[90:91], v[118:119], v[120:121] neg_lo:[0,1] neg_hi:[0,1]
	v_pk_add_f32 v[88:89], v[122:123], v[124:125]
	v_pk_mul_f32 v[96:97], v[46:47], v[90:91]
	v_pk_mul_f32 v[90:91], v[48:49], v[90:91]
	v_pk_fma_f32 v[96:97], v[48:49], v[88:89], v[96:97]
	v_pk_fma_f32 v[90:91], v[46:47], v[88:89], v[90:91] neg_lo:[0,0,1] neg_hi:[0,0,1]
	v_pk_fma_f32 v[88:89], v[128:129], s[48:49], v[126:127] op_sel_hi:[1,0,1] neg_lo:[1,0,0] neg_hi:[1,0,0]
	v_cvt_pk_bf16_f32 v74, v74, v75
	v_pk_fma_f32 v[92:93], v[54:55], v[88:89], v[92:93]
	v_pk_mul_f32 v[88:89], v[56:57], v[88:89]
	v_cvt_pk_bf16_f32 v75, v102, v103
	v_pk_fma_f32 v[86:87], v[54:55], v[86:87], v[88:89] neg_lo:[0,0,1] neg_hi:[0,0,1]
	v_lshl_add_u64 v[88:89], v[0:1], 1, s[0:1]
	s_mov_b32 s0, 0x200000
	v_add_co_u32_e32 v116, vcc, s0, v88
	s_mov_b32 s0, 0x600000
	s_nop 0
	v_addc_co_u32_e32 v117, vcc, 0, v89, vcc
	global_store_dwordx2 v[116:117], v[78:79], off offset:512 sc1
	v_cvt_pk_bf16_f32 v78, v82, v83
	v_add_co_u32_e32 v82, vcc, s7, v88
	v_cvt_pk_bf16_f32 v79, v110, v111
	s_nop 0
	v_addc_co_u32_e32 v83, vcc, 0, v89, vcc
	global_store_dwordx2 v[82:83], v[78:79], off sc1
	v_cvt_pk_bf16_f32 v78, v80, v81
	v_add_co_u32_e32 v80, vcc, s0, v88
	v_cvt_pk_bf16_f32 v70, v70, v71
	s_nop 0
	v_addc_co_u32_e32 v81, vcc, 0, v89, vcc
	global_store_dwordx2 v[80:81], v[74:75], off offset:512 sc1
	v_cvt_pk_bf16_f32 v74, v76, v77
	v_add_co_u32_e32 v76, vcc, s85, v88
	v_cvt_pk_bf16_f32 v71, v98, v99
	s_nop 0
	v_addc_co_u32_e32 v77, vcc, 0, v89, vcc
	s_mov_b32 s0, 0xa00000
	global_store_dwordx2 v[76:77], v[70:71], off offset:512 sc1
	v_cvt_pk_bf16_f32 v70, v72, v73
	v_add_co_u32_e32 v72, vcc, s0, v88
	v_cvt_pk_bf16_f32 v66, v66, v67
	s_nop 0
	v_addc_co_u32_e32 v73, vcc, 0, v89, vcc
	v_cvt_pk_bf16_f32 v67, v94, v95
	s_mov_b32 s0, 0xc00000
	global_store_dwordx2 v[72:73], v[66:67], off offset:512 sc1
	v_cvt_pk_bf16_f32 v66, v68, v69
	v_add_co_u32_e32 v68, vcc, s0, v88
	v_cvt_pk_bf16_f32 v114, v152, v153
	v_cvt_pk_bf16_f32 v115, v146, v147
	v_addc_co_u32_e32 v69, vcc, 0, v89, vcc
	v_cvt_pk_bf16_f32 v62, v62, v63
	v_cvt_pk_bf16_f32 v63, v90, v91
	s_mov_b32 s0, 0xe00000
	global_store_dwordx2 v[88:89], v[114:115], off sc1
	v_cvt_pk_bf16_f32 v114, v148, v149
	v_cvt_pk_bf16_f32 v115, v142, v143
	v_cvt_pk_bf16_f32 v79, v108, v109
	global_store_dwordx2 v[68:69], v[62:63], off offset:512 sc1
	v_cvt_pk_bf16_f32 v62, v64, v65
	v_add_co_u32_e32 v64, vcc, s0, v88
	global_store_dwordx2 v[88:89], v[114:115], off offset:512 sc1
	v_cvt_pk_bf16_f32 v114, v154, v155
	v_cvt_pk_bf16_f32 v115, v156, v157
	global_store_dwordx2 v[82:83], v[78:79], off offset:512 sc1
	v_cvt_pk_bf16_f32 v78, v84, v85
	v_cvt_pk_bf16_f32 v79, v112, v113
	v_cvt_pk_bf16_f32 v75, v104, v105
	v_cvt_pk_bf16_f32 v71, v100, v101
	v_cvt_pk_bf16_f32 v67, v96, v97
	v_cvt_pk_bf16_f32 v63, v92, v93
	v_addc_co_u32_e32 v65, vcc, 0, v89, vcc
	v_cvt_pk_bf16_f32 v60, v60, v61
	v_cvt_pk_bf16_f32 v61, v86, v87
	global_store_dwordx2 v[116:117], v[114:115], off sc1
	global_store_dwordx2 v[80:81], v[78:79], off sc1
	global_store_dwordx2 v[76:77], v[74:75], off sc1
	global_store_dwordx2 v[72:73], v[70:71], off sc1
	global_store_dwordx2 v[68:69], v[66:67], off sc1
	global_store_dwordx2 v[64:65], v[62:63], off sc1
	global_store_dwordx2 v[64:65], v[60:61], off offset:512 sc1
	s_cbranch_scc1 .LBB0_808
